# GEMM tile loops: first K-loop iteration peeled with C=0 on first-touch MFMAs; the 128 accumulator-zeroing moves per tile are gone (5 GEMM loops)
# speedup vs baseline: 1.0068x; 1.0068x over previous
.LBB0_296:
	s_ashr_i32 s9, s8, 31
	v_cmp_lt_i64_e32 vcc, s[12:13], v[180:181]
	s_lshl_b64 s[12:13], s[8:9], 19
	s_add_u32 s12, s29, s12
	s_addc_u32 s13, s30, s13
	s_and_b64 s[14:15], vcc, exec
	s_cselect_b32 s9, s13, s21
	s_cselect_b32 s44, s12, s20
	s_ashr_i32 s7, s6, 31
	s_lshl_b64 s[14:15], s[6:7], 19
	s_add_u32 s14, s31, s14
	s_addc_u32 s15, s33, s15
	s_and_b64 s[24:25], vcc, exec
	s_cselect_b32 s7, s15, s23
	s_cselect_b32 s45, s14, s22
	s_add_u32 s20, s20, 0x40080
	s_addc_u32 s21, s21, 0
	s_add_u32 s46, s22, 0x100
	s_addc_u32 s47, s23, 0
	s_mov_b32 s48, -2
	s_add_u32 s22, s20, 0xfffc0080
	s_addc_u32 s23, s21, -1
	s_add_i32 s49, 0, 0x10000
	v_add_u32_e32 v145, s49, v142
	ds_read_b128 v[146:149], v145
	ds_read_b128 v[150:153], v145 offset:1024
	ds_read_b128 v[154:157], v145 offset:2048
	ds_read_b128 v[158:161], v145 offset:3072
	s_cmp_eq_u32 s48, 12
	s_cselect_b32 s25, s9, s23
	s_cselect_b32 s24, s44, s22
	s_cselect_b32 s23, s7, s47
	s_cselect_b32 s22, s45, s46
	s_add_i32 m0, s19, 0xc000
	ds_read_b128 v[162:165], v144
	ds_read_b128 v[166:169], v144 offset:1024
	ds_read_b128 v[170:173], v144 offset:2048
	ds_read_b128 v[174:177], v144 offset:3072
	ds_read_b128 v[190:193], v144 offset:4096
	ds_read_b128 v[194:197], v144 offset:5120
	ds_read_b128 v[198:201], v144 offset:6144
	ds_read_b128 v[202:205], v144 offset:7168
	global_load_lds_dwordx4 v138, s[20:21]
	s_add_i32 m0, s19, 0xe000
	s_nop 0
	global_load_lds_dwordx4 v140, s[20:21]
	s_waitcnt lgkmcnt(8)
	s_barrier
	s_waitcnt lgkmcnt(0)
	s_waitcnt lgkmcnt(0)
	v_mfma_f32_16x16x32_bf16 v[126:129], v[146:149], v[162:165], 0
	v_mfma_f32_16x16x32_bf16 v[118:121], v[154:157], v[162:165], 0
	v_mfma_f32_16x16x32_bf16 v[110:113], v[146:149], v[170:173], 0
	v_mfma_f32_16x16x32_bf16 v[102:105], v[154:157], v[170:173], 0
	v_mfma_f32_16x16x32_bf16 v[94:97], v[146:149], v[190:193], 0
	v_mfma_f32_16x16x32_bf16 v[86:89], v[154:157], v[190:193], 0
	v_mfma_f32_16x16x32_bf16 v[78:81], v[146:149], v[198:201], 0
	v_mfma_f32_16x16x32_bf16 v[70:73], v[154:157], v[198:201], 0
	v_mfma_f32_16x16x32_bf16 v[126:129], v[150:153], v[166:169], v[126:129]
	v_mfma_f32_16x16x32_bf16 v[118:121], v[158:161], v[166:169], v[118:121]
	v_mfma_f32_16x16x32_bf16 v[110:113], v[150:153], v[174:177], v[110:113]
	v_mfma_f32_16x16x32_bf16 v[102:105], v[158:161], v[174:177], v[102:105]
	v_mfma_f32_16x16x32_bf16 v[94:97], v[150:153], v[194:197], v[94:97]
	v_mfma_f32_16x16x32_bf16 v[86:89], v[158:161], v[194:197], v[86:89]
	v_mfma_f32_16x16x32_bf16 v[78:81], v[150:153], v[202:205], v[78:81]
	v_mfma_f32_16x16x32_bf16 v[70:73], v[158:161], v[202:205], v[70:73]
	s_barrier
	s_add_i32 s54, 0, 0x14000
	s_add_i32 s49, s49, s35
	v_add_u32_e32 v145, s54, v142
	s_add_u32 s64, s22, 0x80
	s_addc_u32 s65, s23, 0
	s_mov_b32 m0, s49
	ds_read_b128 v[206:209], v145
	ds_read_b128 v[210:213], v145 offset:1024
	ds_read_b128 v[214:217], v145 offset:2048
	ds_read_b128 v[218:221], v145 offset:3072
	global_load_lds_dwordx4 v134, s[22:23]
	s_add_i32 m0, s49, 0x2000
	s_nop 0
	global_load_lds_dwordx4 v130, s[22:23]
	s_barrier
	s_waitcnt lgkmcnt(0)
	s_waitcnt lgkmcnt(0)
	v_mfma_f32_16x16x32_bf16 v[122:125], v[206:209], v[162:165], 0
	v_mfma_f32_16x16x32_bf16 v[114:117], v[214:217], v[162:165], 0
	v_mfma_f32_16x16x32_bf16 v[106:109], v[206:209], v[170:173], 0
	v_mfma_f32_16x16x32_bf16 v[98:101], v[214:217], v[170:173], 0
	v_mfma_f32_16x16x32_bf16 v[90:93], v[206:209], v[190:193], 0
	v_mfma_f32_16x16x32_bf16 v[82:85], v[214:217], v[190:193], 0
	v_mfma_f32_16x16x32_bf16 v[74:77], v[206:209], v[198:201], 0
	v_mfma_f32_16x16x32_bf16 v[66:69], v[214:217], v[198:201], 0
	v_mfma_f32_16x16x32_bf16 v[122:125], v[210:213], v[166:169], v[122:125]
	v_mfma_f32_16x16x32_bf16 v[114:117], v[218:221], v[166:169], v[114:117]
	v_mfma_f32_16x16x32_bf16 v[106:109], v[210:213], v[174:177], v[106:109]
	v_mfma_f32_16x16x32_bf16 v[98:101], v[218:221], v[174:177], v[98:101]
	v_mfma_f32_16x16x32_bf16 v[90:93], v[210:213], v[194:197], v[90:93]
	v_mfma_f32_16x16x32_bf16 v[82:85], v[218:221], v[194:197], v[82:85]
	v_mfma_f32_16x16x32_bf16 v[74:77], v[210:213], v[202:205], v[74:77]
	v_mfma_f32_16x16x32_bf16 v[66:69], v[218:221], v[202:205], v[66:69]
	s_barrier
	s_mov_b32 m0, s19
	s_add_u32 s62, s24, 0x80
	s_addc_u32 s63, s25, 0
	ds_read_b128 v[162:165], v144 offset:16384
	ds_read_b128 v[166:169], v144 offset:17408
	ds_read_b128 v[170:173], v144 offset:18432
	ds_read_b128 v[174:177], v144 offset:19456
	ds_read_b128 v[190:193], v144 offset:20480
	ds_read_b128 v[194:197], v144 offset:21504
	ds_read_b128 v[198:201], v144 offset:22528
	ds_read_b128 v[202:205], v144 offset:23552
	global_load_lds_dwordx4 v136, s[24:25]
	s_mov_b32 m0, s36
	s_nop 0
	global_load_lds_dwordx4 v132, s[24:25]
	s_barrier
	s_waitcnt lgkmcnt(0)
	s_waitcnt lgkmcnt(0)
	v_mfma_f32_16x16x32_bf16 v[62:65], v[146:149], v[162:165], 0
	v_mfma_f32_16x16x32_bf16 v[54:57], v[154:157], v[162:165], 0
	v_mfma_f32_16x16x32_bf16 v[46:49], v[146:149], v[170:173], 0
	v_mfma_f32_16x16x32_bf16 v[38:41], v[154:157], v[170:173], 0
	v_mfma_f32_16x16x32_bf16 v[30:33], v[146:149], v[190:193], 0
	v_mfma_f32_16x16x32_bf16 v[22:25], v[154:157], v[190:193], 0
	v_mfma_f32_16x16x32_bf16 v[14:17], v[146:149], v[198:201], 0
	v_mfma_f32_16x16x32_bf16 v[6:9], v[154:157], v[198:201], 0
	v_mfma_f32_16x16x32_bf16 v[62:65], v[150:153], v[166:169], v[62:65]
	v_mfma_f32_16x16x32_bf16 v[54:57], v[158:161], v[166:169], v[54:57]
	v_mfma_f32_16x16x32_bf16 v[46:49], v[150:153], v[174:177], v[46:49]
	v_mfma_f32_16x16x32_bf16 v[38:41], v[158:161], v[174:177], v[38:41]
	v_mfma_f32_16x16x32_bf16 v[30:33], v[150:153], v[194:197], v[30:33]
	v_mfma_f32_16x16x32_bf16 v[22:25], v[158:161], v[194:197], v[22:25]
	v_mfma_f32_16x16x32_bf16 v[14:17], v[150:153], v[202:205], v[14:17]
	v_mfma_f32_16x16x32_bf16 v[6:9], v[158:161], v[202:205], v[6:9]
	s_barrier
	s_add_u32 s50, s22, 0x40000
	s_addc_u32 s51, s23, 0
	s_add_i32 s49, s54, s35
	s_mov_b32 m0, s49
	s_nop 0
	global_load_lds_dwordx4 v134, s[50:51]
	s_add_i32 m0, s49, 0x2000
	s_nop 0
	global_load_lds_dwordx4 v130, s[50:51]
	s_waitcnt vmcnt(6)
	s_barrier
	v_mfma_f32_16x16x32_bf16 v[58:61], v[206:209], v[162:165], 0
	v_mfma_f32_16x16x32_bf16 v[50:53], v[214:217], v[162:165], 0
	v_mfma_f32_16x16x32_bf16 v[42:45], v[206:209], v[170:173], 0
	v_mfma_f32_16x16x32_bf16 v[34:37], v[214:217], v[170:173], 0
	v_mfma_f32_16x16x32_bf16 v[26:29], v[206:209], v[190:193], 0
	v_mfma_f32_16x16x32_bf16 v[18:21], v[214:217], v[190:193], 0
	v_mfma_f32_16x16x32_bf16 v[10:13], v[206:209], v[198:201], 0
	v_mfma_f32_16x16x32_bf16 v[2:5], v[214:217], v[198:201], 0
	v_mfma_f32_16x16x32_bf16 v[58:61], v[210:213], v[166:169], v[58:61]
	v_mfma_f32_16x16x32_bf16 v[50:53], v[218:221], v[166:169], v[50:53]
	v_mfma_f32_16x16x32_bf16 v[42:45], v[210:213], v[174:177], v[42:45]
	v_mfma_f32_16x16x32_bf16 v[34:37], v[218:221], v[174:177], v[34:37]
	v_mfma_f32_16x16x32_bf16 v[26:29], v[210:213], v[194:197], v[26:29]
	v_mfma_f32_16x16x32_bf16 v[18:21], v[218:221], v[194:197], v[18:21]
	v_mfma_f32_16x16x32_bf16 v[10:13], v[210:213], v[202:205], v[10:13]
	v_mfma_f32_16x16x32_bf16 v[2:5], v[218:221], v[202:205], v[2:5]
	s_barrier
	s_add_i32 s49, 0, 0x18000
	v_add_u32_e32 v145, s49, v142
	ds_read_b128 v[146:149], v145
	ds_read_b128 v[150:153], v145 offset:1024
	ds_read_b128 v[154:157], v145 offset:2048
	ds_read_b128 v[158:161], v145 offset:3072
	s_add_u32 s24, s24, 0x40000
	s_addc_u32 s25, s25, 0
	s_mov_b32 m0, s37
	ds_read_b128 v[162:165], v144 offset:32768
	ds_read_b128 v[166:169], v144 offset:33792
	ds_read_b128 v[170:173], v144 offset:34816
	ds_read_b128 v[174:177], v144 offset:35840
	ds_read_b128 v[190:193], v144 offset:36864
	ds_read_b128 v[194:197], v144 offset:37888
	ds_read_b128 v[198:201], v144 offset:38912
	ds_read_b128 v[202:205], v144 offset:39936
	global_load_lds_dwordx4 v136, s[24:25]
	s_mov_b32 m0, s38
	s_nop 0
	global_load_lds_dwordx4 v132, s[24:25]
	s_waitcnt lgkmcnt(8)
	s_barrier
	s_waitcnt lgkmcnt(0)
	s_waitcnt lgkmcnt(0)
	v_mfma_f32_16x16x32_bf16 v[126:129], v[146:149], v[162:165], v[126:129]
	v_mfma_f32_16x16x32_bf16 v[118:121], v[154:157], v[162:165], v[118:121]
	v_mfma_f32_16x16x32_bf16 v[110:113], v[146:149], v[170:173], v[110:113]
	v_mfma_f32_16x16x32_bf16 v[102:105], v[154:157], v[170:173], v[102:105]
	v_mfma_f32_16x16x32_bf16 v[94:97], v[146:149], v[190:193], v[94:97]
	v_mfma_f32_16x16x32_bf16 v[86:89], v[154:157], v[190:193], v[86:89]
	v_mfma_f32_16x16x32_bf16 v[78:81], v[146:149], v[198:201], v[78:81]
	v_mfma_f32_16x16x32_bf16 v[70:73], v[154:157], v[198:201], v[70:73]
	v_mfma_f32_16x16x32_bf16 v[126:129], v[150:153], v[166:169], v[126:129]
	v_mfma_f32_16x16x32_bf16 v[118:121], v[158:161], v[166:169], v[118:121]
	v_mfma_f32_16x16x32_bf16 v[110:113], v[150:153], v[174:177], v[110:113]
	v_mfma_f32_16x16x32_bf16 v[102:105], v[158:161], v[174:177], v[102:105]
	v_mfma_f32_16x16x32_bf16 v[94:97], v[150:153], v[194:197], v[94:97]
	v_mfma_f32_16x16x32_bf16 v[86:89], v[158:161], v[194:197], v[86:89]
	v_mfma_f32_16x16x32_bf16 v[78:81], v[150:153], v[202:205], v[78:81]
	v_mfma_f32_16x16x32_bf16 v[70:73], v[158:161], v[202:205], v[70:73]
	s_barrier
	s_add_i32 s24, 0, 0x1c000
	s_add_i32 s25, s49, s35
	v_add_u32_e32 v145, s24, v142
	s_mov_b32 m0, s25
	ds_read_b128 v[206:209], v145
	ds_read_b128 v[210:213], v145 offset:1024
	ds_read_b128 v[214:217], v145 offset:2048
	ds_read_b128 v[218:221], v145 offset:3072
	global_load_lds_dwordx4 v134, s[64:65]
	s_add_i32 m0, s25, 0x2000
	s_nop 0
	global_load_lds_dwordx4 v130, s[64:65]
	s_barrier
	s_waitcnt lgkmcnt(0)
	s_waitcnt lgkmcnt(0)
	v_mfma_f32_16x16x32_bf16 v[122:125], v[206:209], v[162:165], v[122:125]
	v_mfma_f32_16x16x32_bf16 v[114:117], v[214:217], v[162:165], v[114:117]
	v_mfma_f32_16x16x32_bf16 v[106:109], v[206:209], v[170:173], v[106:109]
	v_mfma_f32_16x16x32_bf16 v[98:101], v[214:217], v[170:173], v[98:101]
	v_mfma_f32_16x16x32_bf16 v[90:93], v[206:209], v[190:193], v[90:93]
	v_mfma_f32_16x16x32_bf16 v[82:85], v[214:217], v[190:193], v[82:85]
	v_mfma_f32_16x16x32_bf16 v[74:77], v[206:209], v[198:201], v[74:77]
	v_mfma_f32_16x16x32_bf16 v[66:69], v[214:217], v[198:201], v[66:69]
	v_mfma_f32_16x16x32_bf16 v[122:125], v[210:213], v[166:169], v[122:125]
	v_mfma_f32_16x16x32_bf16 v[114:117], v[218:221], v[166:169], v[114:117]
	v_mfma_f32_16x16x32_bf16 v[106:109], v[210:213], v[174:177], v[106:109]
	v_mfma_f32_16x16x32_bf16 v[98:101], v[218:221], v[174:177], v[98:101]
	v_mfma_f32_16x16x32_bf16 v[90:93], v[210:213], v[194:197], v[90:93]
	v_mfma_f32_16x16x32_bf16 v[82:85], v[218:221], v[194:197], v[82:85]
	v_mfma_f32_16x16x32_bf16 v[74:77], v[210:213], v[202:205], v[74:77]
	v_mfma_f32_16x16x32_bf16 v[66:69], v[218:221], v[202:205], v[66:69]
	s_barrier
	s_mov_b32 m0, s39
	ds_read_b128 v[162:165], v144 offset:49152
	ds_read_b128 v[166:169], v144 offset:50176
	ds_read_b128 v[170:173], v144 offset:51200
	ds_read_b128 v[174:177], v144 offset:52224
	ds_read_b128 v[190:193], v144 offset:53248
	ds_read_b128 v[194:197], v144 offset:54272
	ds_read_b128 v[198:201], v144 offset:55296
	ds_read_b128 v[202:205], v144 offset:56320
	global_load_lds_dwordx4 v136, s[62:63]
	s_mov_b32 m0, s40
	s_nop 0
	global_load_lds_dwordx4 v132, s[62:63]
	s_barrier
	s_waitcnt lgkmcnt(0)
	s_waitcnt lgkmcnt(0)
	v_mfma_f32_16x16x32_bf16 v[62:65], v[146:149], v[162:165], v[62:65]
	v_mfma_f32_16x16x32_bf16 v[54:57], v[154:157], v[162:165], v[54:57]
	v_mfma_f32_16x16x32_bf16 v[46:49], v[146:149], v[170:173], v[46:49]
	v_mfma_f32_16x16x32_bf16 v[38:41], v[154:157], v[170:173], v[38:41]
	v_mfma_f32_16x16x32_bf16 v[30:33], v[146:149], v[190:193], v[30:33]
	v_mfma_f32_16x16x32_bf16 v[22:25], v[154:157], v[190:193], v[22:25]
	v_mfma_f32_16x16x32_bf16 v[14:17], v[146:149], v[198:201], v[14:17]
	v_mfma_f32_16x16x32_bf16 v[6:9], v[154:157], v[198:201], v[6:9]
	v_mfma_f32_16x16x32_bf16 v[62:65], v[150:153], v[166:169], v[62:65]
	v_mfma_f32_16x16x32_bf16 v[54:57], v[158:161], v[166:169], v[54:57]
	v_mfma_f32_16x16x32_bf16 v[46:49], v[150:153], v[174:177], v[46:49]
	v_mfma_f32_16x16x32_bf16 v[38:41], v[158:161], v[174:177], v[38:41]
	v_mfma_f32_16x16x32_bf16 v[30:33], v[150:153], v[194:197], v[30:33]
	v_mfma_f32_16x16x32_bf16 v[22:25], v[158:161], v[194:197], v[22:25]
	v_mfma_f32_16x16x32_bf16 v[14:17], v[150:153], v[202:205], v[14:17]
	v_mfma_f32_16x16x32_bf16 v[6:9], v[158:161], v[202:205], v[6:9]
	s_barrier
	s_add_u32 s22, s22, 0x40080
	s_addc_u32 s23, s23, 0
	s_add_i32 s24, s24, s35
	s_mov_b32 m0, s24
	s_nop 0
	global_load_lds_dwordx4 v134, s[22:23]
	s_add_i32 m0, s24, 0x2000
	s_nop 0
	global_load_lds_dwordx4 v130, s[22:23]
	s_waitcnt vmcnt(6)
	s_barrier
	v_mfma_f32_16x16x32_bf16 v[58:61], v[206:209], v[162:165], v[58:61]
	v_mfma_f32_16x16x32_bf16 v[50:53], v[214:217], v[162:165], v[50:53]
	v_mfma_f32_16x16x32_bf16 v[42:45], v[206:209], v[170:173], v[42:45]
	v_mfma_f32_16x16x32_bf16 v[34:37], v[214:217], v[170:173], v[34:37]
	v_mfma_f32_16x16x32_bf16 v[26:29], v[206:209], v[190:193], v[26:29]
	v_mfma_f32_16x16x32_bf16 v[18:21], v[214:217], v[190:193], v[18:21]
	v_mfma_f32_16x16x32_bf16 v[10:13], v[206:209], v[198:201], v[10:13]
	v_mfma_f32_16x16x32_bf16 v[2:5], v[214:217], v[198:201], v[2:5]
	v_mfma_f32_16x16x32_bf16 v[58:61], v[210:213], v[166:169], v[58:61]
	v_mfma_f32_16x16x32_bf16 v[50:53], v[218:221], v[166:169], v[50:53]
	v_mfma_f32_16x16x32_bf16 v[42:45], v[210:213], v[174:177], v[42:45]
	v_mfma_f32_16x16x32_bf16 v[34:37], v[218:221], v[174:177], v[34:37]
	v_mfma_f32_16x16x32_bf16 v[26:29], v[210:213], v[194:197], v[26:29]
	v_mfma_f32_16x16x32_bf16 v[18:21], v[218:221], v[194:197], v[18:21]
	v_mfma_f32_16x16x32_bf16 v[10:13], v[210:213], v[202:205], v[10:13]
	v_mfma_f32_16x16x32_bf16 v[2:5], v[218:221], v[202:205], v[2:5]
	s_barrier
	s_add_i32 s48, s48, 2
	s_add_u32 s20, s20, 0x100
	s_addc_u32 s21, s21, 0
	s_add_u32 s46, s46, 0x100
	s_addc_u32 s47, s47, 0

.LBB0_373:
	s_add_u32 s46, s16, 0x100
	s_addc_u32 s47, s17, 0
	s_mov_b32 s48, -2
	s_add_u32 s16, s14, 0x100
	s_addc_u32 s17, s15, 0
	s_add_i32 s49, 0, 0x10000
	v_add_u32_e32 v154, s49, v164
	ds_read_b128 v[142:145], v154
	ds_read_b128 v[146:149], v154 offset:1024
	ds_read_b128 v[150:153], v154 offset:2048
	ds_read_b128 v[154:157], v154 offset:3072
	s_cmp_eq_u32 s48, 40
	s_cselect_b32 s21, s7, s17
	s_cselect_b32 s20, s6, s16
	s_cselect_b32 s19, s9, s47
	s_cselect_b32 s18, s8, s46
	v_lshl_add_u64 v[162:163], s[14:15], 0, v[138:139]
	s_add_i32 m0, s35, 0xc000
	ds_read_b128 v[158:161], v166
	ds_read_b128 v[168:171], v166 offset:1024
	ds_read_b128 v[172:175], v166 offset:2048
	ds_read_b128 v[190:193], v166 offset:3072
	ds_read_b128 v[194:197], v166 offset:4096
	ds_read_b128 v[198:201], v166 offset:5120
	ds_read_b128 v[202:205], v166 offset:6144
	ds_read_b128 v[206:209], v166 offset:7168
	global_load_lds_dwordx4 v[162:163], off
	v_lshl_add_u64 v[162:163], s[14:15], 0, v[140:141]
	s_add_i32 m0, s35, 0xe000
	s_nop 0
	global_load_lds_dwordx4 v[162:163], off
	s_waitcnt lgkmcnt(8)
	s_barrier
	s_waitcnt lgkmcnt(0)
	s_waitcnt lgkmcnt(0)
	v_mfma_f32_16x16x32_bf16 v[126:129], v[142:145], v[158:161], 0
	v_mfma_f32_16x16x32_bf16 v[122:125], v[150:153], v[158:161], 0
	v_mfma_f32_16x16x32_bf16 v[110:113], v[142:145], v[172:175], 0
	v_mfma_f32_16x16x32_bf16 v[106:109], v[150:153], v[172:175], 0
	v_mfma_f32_16x16x32_bf16 v[94:97], v[142:145], v[194:197], 0
	v_mfma_f32_16x16x32_bf16 v[90:93], v[150:153], v[194:197], 0
	v_mfma_f32_16x16x32_bf16 v[78:81], v[142:145], v[202:205], 0
	v_mfma_f32_16x16x32_bf16 v[74:77], v[150:153], v[202:205], 0
	v_mfma_f32_16x16x32_bf16 v[126:129], v[146:149], v[168:171], v[126:129]
	v_mfma_f32_16x16x32_bf16 v[122:125], v[154:157], v[168:171], v[122:125]
	v_mfma_f32_16x16x32_bf16 v[110:113], v[146:149], v[190:193], v[110:113]
	v_mfma_f32_16x16x32_bf16 v[106:109], v[154:157], v[190:193], v[106:109]
	v_mfma_f32_16x16x32_bf16 v[94:97], v[146:149], v[198:201], v[94:97]
	v_mfma_f32_16x16x32_bf16 v[90:93], v[154:157], v[198:201], v[90:93]
	v_mfma_f32_16x16x32_bf16 v[78:81], v[146:149], v[206:209], v[78:81]
	v_mfma_f32_16x16x32_bf16 v[74:77], v[154:157], v[206:209], v[74:77]
	s_barrier
	s_add_i32 s50, 0, 0x14000
	v_add_u32_e32 v162, s50, v164
	s_add_i32 s14, s49, s34
	ds_read_b128 v[210:213], v162
	ds_read_b128 v[214:217], v162 offset:1024
	ds_read_b128 v[218:221], v162 offset:2048
	ds_read_b128 v[222:225], v162 offset:3072
	s_add_u32 s64, s18, 0x80
	s_addc_u32 s65, s19, 0
	s_mov_b32 m0, s14
	s_nop 0
	global_load_lds_dwordx4 v132, s[18:19]
	s_add_i32 m0, s14, 0x2000
	s_nop 0
	global_load_lds_dwordx4 v136, s[18:19]
	s_barrier
	s_waitcnt lgkmcnt(0)
	s_waitcnt lgkmcnt(0)
	v_mfma_f32_16x16x32_bf16 v[118:121], v[210:213], v[158:161], 0
	v_mfma_f32_16x16x32_bf16 v[114:117], v[218:221], v[158:161], 0
	v_mfma_f32_16x16x32_bf16 v[102:105], v[210:213], v[172:175], 0
	v_mfma_f32_16x16x32_bf16 v[98:101], v[218:221], v[172:175], 0
	v_mfma_f32_16x16x32_bf16 v[86:89], v[210:213], v[194:197], 0
	v_mfma_f32_16x16x32_bf16 v[82:85], v[218:221], v[194:197], 0
	v_mfma_f32_16x16x32_bf16 v[70:73], v[210:213], v[202:205], 0
	v_mfma_f32_16x16x32_bf16 v[66:69], v[218:221], v[202:205], 0
	v_mfma_f32_16x16x32_bf16 v[118:121], v[214:217], v[168:171], v[118:121]
	v_mfma_f32_16x16x32_bf16 v[114:117], v[222:225], v[168:171], v[114:117]
	v_mfma_f32_16x16x32_bf16 v[102:105], v[214:217], v[190:193], v[102:105]
	v_mfma_f32_16x16x32_bf16 v[98:101], v[222:225], v[190:193], v[98:101]
	v_mfma_f32_16x16x32_bf16 v[86:89], v[214:217], v[198:201], v[86:89]
	v_mfma_f32_16x16x32_bf16 v[82:85], v[222:225], v[198:201], v[82:85]
	v_mfma_f32_16x16x32_bf16 v[70:73], v[214:217], v[206:209], v[70:73]
	v_mfma_f32_16x16x32_bf16 v[66:69], v[222:225], v[206:209], v[66:69]
	s_barrier
	s_mov_b32 m0, s35
	s_add_u32 s62, s20, 0x80
	s_addc_u32 s63, s21, 0
	ds_read_b128 v[158:161], v166 offset:16384
	ds_read_b128 v[168:171], v166 offset:17408
	ds_read_b128 v[172:175], v166 offset:18432
	ds_read_b128 v[190:193], v166 offset:19456
	ds_read_b128 v[194:197], v166 offset:20480
	ds_read_b128 v[198:201], v166 offset:21504
	ds_read_b128 v[202:205], v166 offset:22528
	ds_read_b128 v[206:209], v166 offset:23552
	global_load_lds_dwordx4 v130, s[20:21]
	s_mov_b32 m0, s36
	s_nop 0
	global_load_lds_dwordx4 v134, s[20:21]
	s_barrier
	s_waitcnt lgkmcnt(0)
	s_waitcnt lgkmcnt(0)
	v_mfma_f32_16x16x32_bf16 v[62:65], v[142:145], v[158:161], 0
	v_mfma_f32_16x16x32_bf16 v[58:61], v[150:153], v[158:161], 0
	v_mfma_f32_16x16x32_bf16 v[46:49], v[142:145], v[172:175], 0
	v_mfma_f32_16x16x32_bf16 v[42:45], v[150:153], v[172:175], 0
	v_mfma_f32_16x16x32_bf16 v[30:33], v[142:145], v[194:197], 0
	v_mfma_f32_16x16x32_bf16 v[26:29], v[150:153], v[194:197], 0
	v_mfma_f32_16x16x32_bf16 v[14:17], v[142:145], v[202:205], 0
	v_mfma_f32_16x16x32_bf16 v[10:13], v[150:153], v[202:205], 0
	v_mfma_f32_16x16x32_bf16 v[62:65], v[146:149], v[168:171], v[62:65]
	v_mfma_f32_16x16x32_bf16 v[58:61], v[154:157], v[168:171], v[58:61]
	v_mfma_f32_16x16x32_bf16 v[46:49], v[146:149], v[190:193], v[46:49]
	v_mfma_f32_16x16x32_bf16 v[42:45], v[154:157], v[190:193], v[42:45]
	v_mfma_f32_16x16x32_bf16 v[30:33], v[146:149], v[198:201], v[30:33]
	v_mfma_f32_16x16x32_bf16 v[26:29], v[154:157], v[198:201], v[26:29]
	v_mfma_f32_16x16x32_bf16 v[14:17], v[146:149], v[206:209], v[14:17]
	v_mfma_f32_16x16x32_bf16 v[10:13], v[154:157], v[206:209], v[10:13]
	s_barrier
	s_add_u32 s14, s18, 0xb0000
	s_addc_u32 s15, s19, 0
	s_add_i32 s49, s50, s34
	s_mov_b32 m0, s49
	s_nop 0
	global_load_lds_dwordx4 v132, s[14:15]
	s_add_i32 m0, s49, 0x2000
	s_nop 0
	global_load_lds_dwordx4 v136, s[14:15]
	s_waitcnt vmcnt(6)
	s_barrier
	v_mfma_f32_16x16x32_bf16 v[54:57], v[210:213], v[158:161], 0
	v_mfma_f32_16x16x32_bf16 v[50:53], v[218:221], v[158:161], 0
	v_mfma_f32_16x16x32_bf16 v[38:41], v[210:213], v[172:175], 0
	v_mfma_f32_16x16x32_bf16 v[34:37], v[218:221], v[172:175], 0
	v_mfma_f32_16x16x32_bf16 v[22:25], v[210:213], v[194:197], 0
	v_mfma_f32_16x16x32_bf16 v[18:21], v[218:221], v[194:197], 0
	v_mfma_f32_16x16x32_bf16 v[6:9], v[210:213], v[202:205], 0
	v_mfma_f32_16x16x32_bf16 v[2:5], v[218:221], v[202:205], 0
	v_mfma_f32_16x16x32_bf16 v[54:57], v[214:217], v[168:171], v[54:57]
	v_mfma_f32_16x16x32_bf16 v[50:53], v[222:225], v[168:171], v[50:53]
	v_mfma_f32_16x16x32_bf16 v[38:41], v[214:217], v[190:193], v[38:41]
	v_mfma_f32_16x16x32_bf16 v[34:37], v[222:225], v[190:193], v[34:37]
	v_mfma_f32_16x16x32_bf16 v[22:25], v[214:217], v[198:201], v[22:25]
	v_mfma_f32_16x16x32_bf16 v[18:21], v[222:225], v[198:201], v[18:21]
	v_mfma_f32_16x16x32_bf16 v[6:9], v[214:217], v[206:209], v[6:9]
	v_mfma_f32_16x16x32_bf16 v[2:5], v[222:225], v[206:209], v[2:5]
	s_barrier
	s_add_i32 s49, 0, 0x18000
	v_add_u32_e32 v154, s49, v164
	ds_read_b128 v[142:145], v154
	ds_read_b128 v[146:149], v154 offset:1024
	ds_read_b128 v[150:153], v154 offset:2048
	ds_read_b128 v[154:157], v154 offset:3072
	s_add_u32 s14, s20, 0xb8000
	s_addc_u32 s15, s21, 0
	s_mov_b32 m0, s37
	ds_read_b128 v[158:161], v166 offset:32768
	ds_read_b128 v[168:171], v166 offset:33792
	ds_read_b128 v[172:175], v166 offset:34816
	ds_read_b128 v[190:193], v166 offset:35840
	ds_read_b128 v[194:197], v166 offset:36864
	ds_read_b128 v[198:201], v166 offset:37888
	ds_read_b128 v[202:205], v166 offset:38912
	ds_read_b128 v[206:209], v166 offset:39936
	global_load_lds_dwordx4 v130, s[14:15]
	s_mov_b32 m0, s38
	s_nop 0
	global_load_lds_dwordx4 v134, s[14:15]
	s_waitcnt lgkmcnt(8)
	s_barrier
	s_waitcnt lgkmcnt(0)
	s_waitcnt lgkmcnt(0)
	v_mfma_f32_16x16x32_bf16 v[126:129], v[142:145], v[158:161], v[126:129]
	v_mfma_f32_16x16x32_bf16 v[122:125], v[150:153], v[158:161], v[122:125]
	v_mfma_f32_16x16x32_bf16 v[110:113], v[142:145], v[172:175], v[110:113]
	v_mfma_f32_16x16x32_bf16 v[106:109], v[150:153], v[172:175], v[106:109]
	v_mfma_f32_16x16x32_bf16 v[94:97], v[142:145], v[194:197], v[94:97]
	v_mfma_f32_16x16x32_bf16 v[90:93], v[150:153], v[194:197], v[90:93]
	v_mfma_f32_16x16x32_bf16 v[78:81], v[142:145], v[202:205], v[78:81]
	v_mfma_f32_16x16x32_bf16 v[74:77], v[150:153], v[202:205], v[74:77]
	v_mfma_f32_16x16x32_bf16 v[126:129], v[146:149], v[168:171], v[126:129]
	v_mfma_f32_16x16x32_bf16 v[122:125], v[154:157], v[168:171], v[122:125]
	v_mfma_f32_16x16x32_bf16 v[110:113], v[146:149], v[190:193], v[110:113]
	v_mfma_f32_16x16x32_bf16 v[106:109], v[154:157], v[190:193], v[106:109]
	v_mfma_f32_16x16x32_bf16 v[94:97], v[146:149], v[198:201], v[94:97]
	v_mfma_f32_16x16x32_bf16 v[90:93], v[154:157], v[198:201], v[90:93]
	v_mfma_f32_16x16x32_bf16 v[78:81], v[146:149], v[206:209], v[78:81]
	v_mfma_f32_16x16x32_bf16 v[74:77], v[154:157], v[206:209], v[74:77]
	s_barrier
	s_add_i32 s20, 0, 0x1c000
	s_add_i32 s14, s49, s34
	v_add_u32_e32 v167, s20, v164
	s_mov_b32 m0, s14
	ds_read_b128 v[210:213], v167
	ds_read_b128 v[214:217], v167 offset:1024
	ds_read_b128 v[218:221], v167 offset:2048
	ds_read_b128 v[222:225], v167 offset:3072
	global_load_lds_dwordx4 v132, s[64:65]
	s_add_i32 m0, s14, 0x2000
	s_nop 0
	global_load_lds_dwordx4 v136, s[64:65]
	s_barrier
	s_waitcnt lgkmcnt(0)
	s_waitcnt lgkmcnt(0)
	v_mfma_f32_16x16x32_bf16 v[118:121], v[210:213], v[158:161], v[118:121]
	v_mfma_f32_16x16x32_bf16 v[114:117], v[218:221], v[158:161], v[114:117]
	v_mfma_f32_16x16x32_bf16 v[102:105], v[210:213], v[172:175], v[102:105]
	v_mfma_f32_16x16x32_bf16 v[98:101], v[218:221], v[172:175], v[98:101]
	v_mfma_f32_16x16x32_bf16 v[86:89], v[210:213], v[194:197], v[86:89]
	v_mfma_f32_16x16x32_bf16 v[82:85], v[218:221], v[194:197], v[82:85]
	v_mfma_f32_16x16x32_bf16 v[70:73], v[210:213], v[202:205], v[70:73]
	v_mfma_f32_16x16x32_bf16 v[66:69], v[218:221], v[202:205], v[66:69]
	v_mfma_f32_16x16x32_bf16 v[118:121], v[214:217], v[168:171], v[118:121]
	v_mfma_f32_16x16x32_bf16 v[114:117], v[222:225], v[168:171], v[114:117]
	v_mfma_f32_16x16x32_bf16 v[102:105], v[214:217], v[190:193], v[102:105]
	v_mfma_f32_16x16x32_bf16 v[98:101], v[222:225], v[190:193], v[98:101]
	v_mfma_f32_16x16x32_bf16 v[86:89], v[214:217], v[198:201], v[86:89]
	v_mfma_f32_16x16x32_bf16 v[82:85], v[222:225], v[198:201], v[82:85]
	v_mfma_f32_16x16x32_bf16 v[70:73], v[214:217], v[206:209], v[70:73]
	v_mfma_f32_16x16x32_bf16 v[66:69], v[222:225], v[206:209], v[66:69]
	s_barrier
	s_mov_b32 m0, s39
	ds_read_b128 v[158:161], v166 offset:49152
	ds_read_b128 v[168:171], v166 offset:50176
	ds_read_b128 v[172:175], v166 offset:51200
	ds_read_b128 v[190:193], v166 offset:52224
	ds_read_b128 v[194:197], v166 offset:53248
	ds_read_b128 v[198:201], v166 offset:54272
	ds_read_b128 v[202:205], v166 offset:55296
	ds_read_b128 v[206:209], v166 offset:56320
	global_load_lds_dwordx4 v130, s[62:63]
	s_mov_b32 m0, s40
	s_nop 0
	global_load_lds_dwordx4 v134, s[62:63]
	s_barrier
	s_waitcnt lgkmcnt(0)
	s_waitcnt lgkmcnt(0)
	v_mfma_f32_16x16x32_bf16 v[62:65], v[142:145], v[158:161], v[62:65]
	v_mfma_f32_16x16x32_bf16 v[58:61], v[150:153], v[158:161], v[58:61]
	v_mfma_f32_16x16x32_bf16 v[46:49], v[142:145], v[172:175], v[46:49]
	v_mfma_f32_16x16x32_bf16 v[42:45], v[150:153], v[172:175], v[42:45]
	v_mfma_f32_16x16x32_bf16 v[30:33], v[142:145], v[194:197], v[30:33]
	v_mfma_f32_16x16x32_bf16 v[26:29], v[150:153], v[194:197], v[26:29]
	v_mfma_f32_16x16x32_bf16 v[14:17], v[142:145], v[202:205], v[14:17]
	v_mfma_f32_16x16x32_bf16 v[10:13], v[150:153], v[202:205], v[10:13]
	v_mfma_f32_16x16x32_bf16 v[62:65], v[146:149], v[168:171], v[62:65]
	v_mfma_f32_16x16x32_bf16 v[58:61], v[154:157], v[168:171], v[58:61]
	v_mfma_f32_16x16x32_bf16 v[46:49], v[146:149], v[190:193], v[46:49]
	v_mfma_f32_16x16x32_bf16 v[42:45], v[154:157], v[190:193], v[42:45]
	v_mfma_f32_16x16x32_bf16 v[30:33], v[146:149], v[198:201], v[30:33]
	v_mfma_f32_16x16x32_bf16 v[26:29], v[154:157], v[198:201], v[26:29]
	v_mfma_f32_16x16x32_bf16 v[14:17], v[146:149], v[206:209], v[14:17]
	v_mfma_f32_16x16x32_bf16 v[10:13], v[154:157], v[206:209], v[10:13]
	s_barrier
	s_add_u32 s14, s18, 0xb0080
	s_addc_u32 s15, s19, 0
	s_add_i32 s18, s20, s34
	s_mov_b32 m0, s18
	s_nop 0
	global_load_lds_dwordx4 v132, s[14:15]
	s_add_i32 m0, s18, 0x2000
	s_nop 0
	global_load_lds_dwordx4 v136, s[14:15]
	s_waitcnt vmcnt(6)
	s_barrier
	v_mfma_f32_16x16x32_bf16 v[54:57], v[210:213], v[158:161], v[54:57]
	v_mfma_f32_16x16x32_bf16 v[50:53], v[218:221], v[158:161], v[50:53]
	v_mfma_f32_16x16x32_bf16 v[38:41], v[210:213], v[172:175], v[38:41]
	v_mfma_f32_16x16x32_bf16 v[34:37], v[218:221], v[172:175], v[34:37]
	v_mfma_f32_16x16x32_bf16 v[22:25], v[210:213], v[194:197], v[22:25]
	v_mfma_f32_16x16x32_bf16 v[18:21], v[218:221], v[194:197], v[18:21]
	v_mfma_f32_16x16x32_bf16 v[6:9], v[210:213], v[202:205], v[6:9]
	v_mfma_f32_16x16x32_bf16 v[2:5], v[218:221], v[202:205], v[2:5]
	v_mfma_f32_16x16x32_bf16 v[54:57], v[214:217], v[168:171], v[54:57]
	v_mfma_f32_16x16x32_bf16 v[50:53], v[222:225], v[168:171], v[50:53]
	v_mfma_f32_16x16x32_bf16 v[38:41], v[214:217], v[190:193], v[38:41]
	v_mfma_f32_16x16x32_bf16 v[34:37], v[222:225], v[190:193], v[34:37]
	v_mfma_f32_16x16x32_bf16 v[22:25], v[214:217], v[198:201], v[22:25]
	v_mfma_f32_16x16x32_bf16 v[18:21], v[222:225], v[198:201], v[18:21]
	v_mfma_f32_16x16x32_bf16 v[6:9], v[214:217], v[206:209], v[6:9]
	v_mfma_f32_16x16x32_bf16 v[2:5], v[222:225], v[206:209], v[2:5]
	s_barrier
	s_add_i32 s48, s48, 2
	s_add_u32 s46, s46, 0x100
	s_addc_u32 s47, s47, 0
	s_mov_b64 s[14:15], s[16:17]

.LBB0_399:
	s_add_u32 s46, s16, 0x100
	s_addc_u32 s47, s17, 0
	s_mov_b32 s48, -2
	s_add_u32 s16, s14, 0x100
	s_addc_u32 s17, s15, 0
	s_add_i32 s49, 0, 0x10000
	v_add_u32_e32 v154, s49, v164
	ds_read_b128 v[142:145], v154
	ds_read_b128 v[146:149], v154 offset:1024
	ds_read_b128 v[150:153], v154 offset:2048
	ds_read_b128 v[154:157], v154 offset:3072
	s_cmp_eq_u32 s48, 40
	s_cselect_b32 s21, s7, s17
	s_cselect_b32 s20, s6, s16
	s_cselect_b32 s19, s9, s47
	s_cselect_b32 s18, s8, s46
	v_lshl_add_u64 v[162:163], s[14:15], 0, v[138:139]
	s_add_i32 m0, s34, 0xc000
	ds_read_b128 v[158:161], v166
	ds_read_b128 v[168:171], v166 offset:1024
	ds_read_b128 v[172:175], v166 offset:2048
	ds_read_b128 v[190:193], v166 offset:3072
	ds_read_b128 v[194:197], v166 offset:4096
	ds_read_b128 v[198:201], v166 offset:5120
	ds_read_b128 v[202:205], v166 offset:6144
	ds_read_b128 v[206:209], v166 offset:7168
	global_load_lds_dwordx4 v[162:163], off
	v_lshl_add_u64 v[162:163], s[14:15], 0, v[140:141]
	s_add_i32 m0, s34, 0xe000
	s_nop 0
	global_load_lds_dwordx4 v[162:163], off
	s_waitcnt lgkmcnt(8)
	s_barrier
	s_waitcnt lgkmcnt(0)
	s_waitcnt lgkmcnt(0)
	v_mfma_f32_16x16x32_bf16 v[126:129], v[142:145], v[158:161], 0
	v_mfma_f32_16x16x32_bf16 v[122:125], v[150:153], v[158:161], 0
	v_mfma_f32_16x16x32_bf16 v[110:113], v[142:145], v[172:175], 0
	v_mfma_f32_16x16x32_bf16 v[106:109], v[150:153], v[172:175], 0
	v_mfma_f32_16x16x32_bf16 v[94:97], v[142:145], v[194:197], 0
	v_mfma_f32_16x16x32_bf16 v[90:93], v[150:153], v[194:197], 0
	v_mfma_f32_16x16x32_bf16 v[78:81], v[142:145], v[202:205], 0
	v_mfma_f32_16x16x32_bf16 v[74:77], v[150:153], v[202:205], 0
	v_mfma_f32_16x16x32_bf16 v[126:129], v[146:149], v[168:171], v[126:129]
	v_mfma_f32_16x16x32_bf16 v[122:125], v[154:157], v[168:171], v[122:125]
	v_mfma_f32_16x16x32_bf16 v[110:113], v[146:149], v[190:193], v[110:113]
	v_mfma_f32_16x16x32_bf16 v[106:109], v[154:157], v[190:193], v[106:109]
	v_mfma_f32_16x16x32_bf16 v[94:97], v[146:149], v[198:201], v[94:97]
	v_mfma_f32_16x16x32_bf16 v[90:93], v[154:157], v[198:201], v[90:93]
	v_mfma_f32_16x16x32_bf16 v[78:81], v[146:149], v[206:209], v[78:81]
	v_mfma_f32_16x16x32_bf16 v[74:77], v[154:157], v[206:209], v[74:77]
	s_barrier
	s_add_i32 s50, 0, 0x14000
	v_add_u32_e32 v162, s50, v164
	s_add_i32 s14, s49, s33
	ds_read_b128 v[210:213], v162
	ds_read_b128 v[214:217], v162 offset:1024
	ds_read_b128 v[218:221], v162 offset:2048
	ds_read_b128 v[222:225], v162 offset:3072
	s_add_u32 s64, s18, 0x80
	s_addc_u32 s65, s19, 0
	s_mov_b32 m0, s14
	s_nop 0
	global_load_lds_dwordx4 v132, s[18:19]
	s_add_i32 m0, s14, 0x2000
	s_nop 0
	global_load_lds_dwordx4 v136, s[18:19]
	s_barrier
	s_waitcnt lgkmcnt(0)
	s_waitcnt lgkmcnt(0)
	v_mfma_f32_16x16x32_bf16 v[118:121], v[210:213], v[158:161], 0
	v_mfma_f32_16x16x32_bf16 v[114:117], v[218:221], v[158:161], 0
	v_mfma_f32_16x16x32_bf16 v[102:105], v[210:213], v[172:175], 0
	v_mfma_f32_16x16x32_bf16 v[98:101], v[218:221], v[172:175], 0
	v_mfma_f32_16x16x32_bf16 v[86:89], v[210:213], v[194:197], 0
	v_mfma_f32_16x16x32_bf16 v[82:85], v[218:221], v[194:197], 0
	v_mfma_f32_16x16x32_bf16 v[70:73], v[210:213], v[202:205], 0
	v_mfma_f32_16x16x32_bf16 v[66:69], v[218:221], v[202:205], 0
	v_mfma_f32_16x16x32_bf16 v[118:121], v[214:217], v[168:171], v[118:121]
	v_mfma_f32_16x16x32_bf16 v[114:117], v[222:225], v[168:171], v[114:117]
	v_mfma_f32_16x16x32_bf16 v[102:105], v[214:217], v[190:193], v[102:105]
	v_mfma_f32_16x16x32_bf16 v[98:101], v[222:225], v[190:193], v[98:101]
	v_mfma_f32_16x16x32_bf16 v[86:89], v[214:217], v[198:201], v[86:89]
	v_mfma_f32_16x16x32_bf16 v[82:85], v[222:225], v[198:201], v[82:85]
	v_mfma_f32_16x16x32_bf16 v[70:73], v[214:217], v[206:209], v[70:73]
	v_mfma_f32_16x16x32_bf16 v[66:69], v[222:225], v[206:209], v[66:69]
	s_barrier
	s_mov_b32 m0, s34
	s_add_u32 s62, s20, 0x80
	s_addc_u32 s63, s21, 0
	ds_read_b128 v[158:161], v166 offset:16384
	ds_read_b128 v[168:171], v166 offset:17408
	ds_read_b128 v[172:175], v166 offset:18432
	ds_read_b128 v[190:193], v166 offset:19456
	ds_read_b128 v[194:197], v166 offset:20480
	ds_read_b128 v[198:201], v166 offset:21504
	ds_read_b128 v[202:205], v166 offset:22528
	ds_read_b128 v[206:209], v166 offset:23552
	global_load_lds_dwordx4 v130, s[20:21]
	s_mov_b32 m0, s35
	s_nop 0
	global_load_lds_dwordx4 v134, s[20:21]
	s_barrier
	s_waitcnt lgkmcnt(0)
	s_waitcnt lgkmcnt(0)
	v_mfma_f32_16x16x32_bf16 v[62:65], v[142:145], v[158:161], 0
	v_mfma_f32_16x16x32_bf16 v[58:61], v[150:153], v[158:161], 0
	v_mfma_f32_16x16x32_bf16 v[46:49], v[142:145], v[172:175], 0
	v_mfma_f32_16x16x32_bf16 v[42:45], v[150:153], v[172:175], 0
	v_mfma_f32_16x16x32_bf16 v[30:33], v[142:145], v[194:197], 0
	v_mfma_f32_16x16x32_bf16 v[26:29], v[150:153], v[194:197], 0
	v_mfma_f32_16x16x32_bf16 v[14:17], v[142:145], v[202:205], 0
	v_mfma_f32_16x16x32_bf16 v[10:13], v[150:153], v[202:205], 0
	v_mfma_f32_16x16x32_bf16 v[62:65], v[146:149], v[168:171], v[62:65]
	v_mfma_f32_16x16x32_bf16 v[58:61], v[154:157], v[168:171], v[58:61]
	v_mfma_f32_16x16x32_bf16 v[46:49], v[146:149], v[190:193], v[46:49]
	v_mfma_f32_16x16x32_bf16 v[42:45], v[154:157], v[190:193], v[42:45]
	v_mfma_f32_16x16x32_bf16 v[30:33], v[146:149], v[198:201], v[30:33]
	v_mfma_f32_16x16x32_bf16 v[26:29], v[154:157], v[198:201], v[26:29]
	v_mfma_f32_16x16x32_bf16 v[14:17], v[146:149], v[206:209], v[14:17]
	v_mfma_f32_16x16x32_bf16 v[10:13], v[154:157], v[206:209], v[10:13]
	s_barrier
	s_add_u32 s14, s18, 0xb0000
	s_addc_u32 s15, s19, 0
	s_add_i32 s49, s50, s33
	s_mov_b32 m0, s49
	s_nop 0
	global_load_lds_dwordx4 v132, s[14:15]
	s_add_i32 m0, s49, 0x2000
	s_nop 0
	global_load_lds_dwordx4 v136, s[14:15]
	s_waitcnt vmcnt(6)
	s_barrier
	v_mfma_f32_16x16x32_bf16 v[54:57], v[210:213], v[158:161], 0
	v_mfma_f32_16x16x32_bf16 v[50:53], v[218:221], v[158:161], 0
	v_mfma_f32_16x16x32_bf16 v[38:41], v[210:213], v[172:175], 0
	v_mfma_f32_16x16x32_bf16 v[34:37], v[218:221], v[172:175], 0
	v_mfma_f32_16x16x32_bf16 v[22:25], v[210:213], v[194:197], 0
	v_mfma_f32_16x16x32_bf16 v[18:21], v[218:221], v[194:197], 0
	v_mfma_f32_16x16x32_bf16 v[6:9], v[210:213], v[202:205], 0
	v_mfma_f32_16x16x32_bf16 v[2:5], v[218:221], v[202:205], 0
	v_mfma_f32_16x16x32_bf16 v[54:57], v[214:217], v[168:171], v[54:57]
	v_mfma_f32_16x16x32_bf16 v[50:53], v[222:225], v[168:171], v[50:53]
	v_mfma_f32_16x16x32_bf16 v[38:41], v[214:217], v[190:193], v[38:41]
	v_mfma_f32_16x16x32_bf16 v[34:37], v[222:225], v[190:193], v[34:37]
	v_mfma_f32_16x16x32_bf16 v[22:25], v[214:217], v[198:201], v[22:25]
	v_mfma_f32_16x16x32_bf16 v[18:21], v[222:225], v[198:201], v[18:21]
	v_mfma_f32_16x16x32_bf16 v[6:9], v[214:217], v[206:209], v[6:9]
	v_mfma_f32_16x16x32_bf16 v[2:5], v[222:225], v[206:209], v[2:5]
	s_barrier
	s_add_i32 s49, 0, 0x18000
	v_add_u32_e32 v154, s49, v164
	ds_read_b128 v[142:145], v154
	ds_read_b128 v[146:149], v154 offset:1024
	ds_read_b128 v[150:153], v154 offset:2048
	ds_read_b128 v[154:157], v154 offset:3072
	s_add_u32 s14, s20, 0xb8000
	s_addc_u32 s15, s21, 0
	s_mov_b32 m0, s36
	ds_read_b128 v[158:161], v166 offset:32768
	ds_read_b128 v[168:171], v166 offset:33792
	ds_read_b128 v[172:175], v166 offset:34816
	ds_read_b128 v[190:193], v166 offset:35840
	ds_read_b128 v[194:197], v166 offset:36864
	ds_read_b128 v[198:201], v166 offset:37888
	ds_read_b128 v[202:205], v166 offset:38912
	ds_read_b128 v[206:209], v166 offset:39936
	global_load_lds_dwordx4 v130, s[14:15]
	s_mov_b32 m0, s37
	s_nop 0
	global_load_lds_dwordx4 v134, s[14:15]
	s_waitcnt lgkmcnt(8)
	s_barrier
	s_waitcnt lgkmcnt(0)
	s_waitcnt lgkmcnt(0)
	v_mfma_f32_16x16x32_bf16 v[126:129], v[142:145], v[158:161], v[126:129]
	v_mfma_f32_16x16x32_bf16 v[122:125], v[150:153], v[158:161], v[122:125]
	v_mfma_f32_16x16x32_bf16 v[110:113], v[142:145], v[172:175], v[110:113]
	v_mfma_f32_16x16x32_bf16 v[106:109], v[150:153], v[172:175], v[106:109]
	v_mfma_f32_16x16x32_bf16 v[94:97], v[142:145], v[194:197], v[94:97]
	v_mfma_f32_16x16x32_bf16 v[90:93], v[150:153], v[194:197], v[90:93]
	v_mfma_f32_16x16x32_bf16 v[78:81], v[142:145], v[202:205], v[78:81]
	v_mfma_f32_16x16x32_bf16 v[74:77], v[150:153], v[202:205], v[74:77]
	v_mfma_f32_16x16x32_bf16 v[126:129], v[146:149], v[168:171], v[126:129]
	v_mfma_f32_16x16x32_bf16 v[122:125], v[154:157], v[168:171], v[122:125]
	v_mfma_f32_16x16x32_bf16 v[110:113], v[146:149], v[190:193], v[110:113]
	v_mfma_f32_16x16x32_bf16 v[106:109], v[154:157], v[190:193], v[106:109]
	v_mfma_f32_16x16x32_bf16 v[94:97], v[146:149], v[198:201], v[94:97]
	v_mfma_f32_16x16x32_bf16 v[90:93], v[154:157], v[198:201], v[90:93]
	v_mfma_f32_16x16x32_bf16 v[78:81], v[146:149], v[206:209], v[78:81]
	v_mfma_f32_16x16x32_bf16 v[74:77], v[154:157], v[206:209], v[74:77]
	s_barrier
	s_add_i32 s20, 0, 0x1c000
	s_add_i32 s14, s49, s33
	v_add_u32_e32 v167, s20, v164
	s_mov_b32 m0, s14
	ds_read_b128 v[210:213], v167
	ds_read_b128 v[214:217], v167 offset:1024
	ds_read_b128 v[218:221], v167 offset:2048
	ds_read_b128 v[222:225], v167 offset:3072
	global_load_lds_dwordx4 v132, s[64:65]
	s_add_i32 m0, s14, 0x2000
	s_nop 0
	global_load_lds_dwordx4 v136, s[64:65]
	s_barrier
	s_waitcnt lgkmcnt(0)
	s_waitcnt lgkmcnt(0)
	v_mfma_f32_16x16x32_bf16 v[118:121], v[210:213], v[158:161], v[118:121]
	v_mfma_f32_16x16x32_bf16 v[114:117], v[218:221], v[158:161], v[114:117]
	v_mfma_f32_16x16x32_bf16 v[102:105], v[210:213], v[172:175], v[102:105]
	v_mfma_f32_16x16x32_bf16 v[98:101], v[218:221], v[172:175], v[98:101]
	v_mfma_f32_16x16x32_bf16 v[86:89], v[210:213], v[194:197], v[86:89]
	v_mfma_f32_16x16x32_bf16 v[82:85], v[218:221], v[194:197], v[82:85]
	v_mfma_f32_16x16x32_bf16 v[70:73], v[210:213], v[202:205], v[70:73]
	v_mfma_f32_16x16x32_bf16 v[66:69], v[218:221], v[202:205], v[66:69]
	v_mfma_f32_16x16x32_bf16 v[118:121], v[214:217], v[168:171], v[118:121]
	v_mfma_f32_16x16x32_bf16 v[114:117], v[222:225], v[168:171], v[114:117]
	v_mfma_f32_16x16x32_bf16 v[102:105], v[214:217], v[190:193], v[102:105]
	v_mfma_f32_16x16x32_bf16 v[98:101], v[222:225], v[190:193], v[98:101]
	v_mfma_f32_16x16x32_bf16 v[86:89], v[214:217], v[198:201], v[86:89]
	v_mfma_f32_16x16x32_bf16 v[82:85], v[222:225], v[198:201], v[82:85]
	v_mfma_f32_16x16x32_bf16 v[70:73], v[214:217], v[206:209], v[70:73]
	v_mfma_f32_16x16x32_bf16 v[66:69], v[222:225], v[206:209], v[66:69]
	s_barrier
	s_mov_b32 m0, s38
	ds_read_b128 v[158:161], v166 offset:49152
	ds_read_b128 v[168:171], v166 offset:50176
	ds_read_b128 v[172:175], v166 offset:51200
	ds_read_b128 v[190:193], v166 offset:52224
	ds_read_b128 v[194:197], v166 offset:53248
	ds_read_b128 v[198:201], v166 offset:54272
	ds_read_b128 v[202:205], v166 offset:55296
	ds_read_b128 v[206:209], v166 offset:56320
	global_load_lds_dwordx4 v130, s[62:63]
	s_mov_b32 m0, s39
	s_nop 0
	global_load_lds_dwordx4 v134, s[62:63]
	s_barrier
	s_waitcnt lgkmcnt(0)
	s_waitcnt lgkmcnt(0)
	v_mfma_f32_16x16x32_bf16 v[62:65], v[142:145], v[158:161], v[62:65]
	v_mfma_f32_16x16x32_bf16 v[58:61], v[150:153], v[158:161], v[58:61]
	v_mfma_f32_16x16x32_bf16 v[46:49], v[142:145], v[172:175], v[46:49]
	v_mfma_f32_16x16x32_bf16 v[42:45], v[150:153], v[172:175], v[42:45]
	v_mfma_f32_16x16x32_bf16 v[30:33], v[142:145], v[194:197], v[30:33]
	v_mfma_f32_16x16x32_bf16 v[26:29], v[150:153], v[194:197], v[26:29]
	v_mfma_f32_16x16x32_bf16 v[14:17], v[142:145], v[202:205], v[14:17]
	v_mfma_f32_16x16x32_bf16 v[10:13], v[150:153], v[202:205], v[10:13]
	v_mfma_f32_16x16x32_bf16 v[62:65], v[146:149], v[168:171], v[62:65]
	v_mfma_f32_16x16x32_bf16 v[58:61], v[154:157], v[168:171], v[58:61]
	v_mfma_f32_16x16x32_bf16 v[46:49], v[146:149], v[190:193], v[46:49]
	v_mfma_f32_16x16x32_bf16 v[42:45], v[154:157], v[190:193], v[42:45]
	v_mfma_f32_16x16x32_bf16 v[30:33], v[146:149], v[198:201], v[30:33]
	v_mfma_f32_16x16x32_bf16 v[26:29], v[154:157], v[198:201], v[26:29]
	v_mfma_f32_16x16x32_bf16 v[14:17], v[146:149], v[206:209], v[14:17]
	v_mfma_f32_16x16x32_bf16 v[10:13], v[154:157], v[206:209], v[10:13]
	s_barrier
	s_add_u32 s14, s18, 0xb0080
	s_addc_u32 s15, s19, 0
	s_add_i32 s18, s20, s33
	s_mov_b32 m0, s18
	s_nop 0
	global_load_lds_dwordx4 v132, s[14:15]
	s_add_i32 m0, s18, 0x2000
	s_nop 0
	global_load_lds_dwordx4 v136, s[14:15]
	s_waitcnt vmcnt(6)
	s_barrier
	v_mfma_f32_16x16x32_bf16 v[54:57], v[210:213], v[158:161], v[54:57]
	v_mfma_f32_16x16x32_bf16 v[50:53], v[218:221], v[158:161], v[50:53]
	v_mfma_f32_16x16x32_bf16 v[38:41], v[210:213], v[172:175], v[38:41]
	v_mfma_f32_16x16x32_bf16 v[34:37], v[218:221], v[172:175], v[34:37]
	v_mfma_f32_16x16x32_bf16 v[22:25], v[210:213], v[194:197], v[22:25]
	v_mfma_f32_16x16x32_bf16 v[18:21], v[218:221], v[194:197], v[18:21]
	v_mfma_f32_16x16x32_bf16 v[6:9], v[210:213], v[202:205], v[6:9]
	v_mfma_f32_16x16x32_bf16 v[2:5], v[218:221], v[202:205], v[2:5]
	v_mfma_f32_16x16x32_bf16 v[54:57], v[214:217], v[168:171], v[54:57]
	v_mfma_f32_16x16x32_bf16 v[50:53], v[222:225], v[168:171], v[50:53]
	v_mfma_f32_16x16x32_bf16 v[38:41], v[214:217], v[190:193], v[38:41]
	v_mfma_f32_16x16x32_bf16 v[34:37], v[222:225], v[190:193], v[34:37]
	v_mfma_f32_16x16x32_bf16 v[22:25], v[214:217], v[198:201], v[22:25]
	v_mfma_f32_16x16x32_bf16 v[18:21], v[222:225], v[198:201], v[18:21]
	v_mfma_f32_16x16x32_bf16 v[6:9], v[214:217], v[206:209], v[6:9]
	v_mfma_f32_16x16x32_bf16 v[2:5], v[222:225], v[206:209], v[2:5]
	s_barrier
	s_add_i32 s48, s48, 2
	s_add_u32 s46, s46, 0x100
	s_addc_u32 s47, s47, 0
	s_mov_b64 s[14:15], s[16:17]

.LBB0_527:
	v_mov_b64_e32 v[2:3], s[80:81]
	s_ashr_i32 s15, s14, 31
	v_cmp_lt_i64_e32 vcc, s[16:17], v[2:3]
	s_lshl_b64 s[16:17], s[14:15], 19
	s_add_u32 s16, s29, s16
	s_addc_u32 s17, s30, s17
	s_and_b64 s[18:19], vcc, exec
	s_cselect_b32 s11, s17, s21
	s_cselect_b32 s15, s16, s20
	s_ashr_i32 s13, s12, 31
	s_lshl_b64 s[18:19], s[12:13], 19
	s_add_u32 s18, s31, s18
	s_addc_u32 s19, s33, s19
	s_and_b64 s[24:25], vcc, exec
	s_cselect_b32 s13, s19, s23
	s_cselect_b32 s51, s18, s22
	s_add_u32 s20, s20, 0x40080
	s_addc_u32 s21, s21, 0
	s_add_u32 s52, s22, 0x100
	s_addc_u32 s53, s23, 0
	s_mov_b32 s54, -2
	s_add_u32 s22, s20, 0xfffc0080
	s_addc_u32 s23, s21, -1
	s_add_i32 s55, 0, 0x10000
	v_add_u32_e32 v144, s55, v146
	ds_read_b128 v[150:153], v144
	ds_read_b128 v[154:157], v144 offset:1024
	ds_read_b128 v[158:161], v144 offset:2048
	ds_read_b128 v[162:165], v144 offset:3072
	s_cmp_eq_u32 s54, 12
	s_cselect_b32 s25, s11, s23
	s_cselect_b32 s24, s15, s22
	s_cselect_b32 s23, s13, s53
	s_cselect_b32 s22, s51, s52
	s_add_i32 m0, s41, 0xc000
	ds_read_b128 v[166:169], v148
	ds_read_b128 v[170:173], v148 offset:1024
	ds_read_b128 v[174:177], v148 offset:2048
	ds_read_b128 v[190:193], v148 offset:3072
	ds_read_b128 v[194:197], v148 offset:4096
	ds_read_b128 v[198:201], v148 offset:5120
	ds_read_b128 v[202:205], v148 offset:6144
	ds_read_b128 v[206:209], v148 offset:7168
	global_load_lds_dwordx4 v140, s[20:21]
	v_lshl_add_u64 v[144:145], s[20:21], 0, v[142:143]
	s_add_i32 m0, s41, 0xe000
	s_nop 0
	global_load_lds_dwordx4 v[144:145], off
	s_waitcnt lgkmcnt(8)
	s_barrier
	s_waitcnt lgkmcnt(0)
	s_waitcnt lgkmcnt(0)
	v_mfma_f32_16x16x32_bf16 v[86:89], v[150:153], v[166:169], 0
	v_mfma_f32_16x16x32_bf16 v[82:85], v[158:161], v[166:169], 0
	v_mfma_f32_16x16x32_bf16 v[78:81], v[150:153], v[174:177], 0
	v_mfma_f32_16x16x32_bf16 v[74:77], v[158:161], v[174:177], 0
	v_mfma_f32_16x16x32_bf16 v[62:65], v[150:153], v[194:197], 0
	v_mfma_f32_16x16x32_bf16 v[58:61], v[158:161], v[194:197], 0
	v_mfma_f32_16x16x32_bf16 v[54:57], v[150:153], v[202:205], 0
	v_mfma_f32_16x16x32_bf16 v[50:53], v[158:161], v[202:205], 0
	v_mfma_f32_16x16x32_bf16 v[86:89], v[154:157], v[170:173], v[86:89]
	v_mfma_f32_16x16x32_bf16 v[82:85], v[162:165], v[170:173], v[82:85]
	v_mfma_f32_16x16x32_bf16 v[78:81], v[154:157], v[190:193], v[78:81]
	v_mfma_f32_16x16x32_bf16 v[74:77], v[162:165], v[190:193], v[74:77]
	v_mfma_f32_16x16x32_bf16 v[62:65], v[154:157], v[198:201], v[62:65]
	v_mfma_f32_16x16x32_bf16 v[58:61], v[162:165], v[198:201], v[58:61]
	v_mfma_f32_16x16x32_bf16 v[54:57], v[154:157], v[206:209], v[54:57]
	v_mfma_f32_16x16x32_bf16 v[50:53], v[162:165], v[206:209], v[50:53]
	s_barrier
	s_add_i32 s58, 0, 0x14000
	v_add_u32_e32 v144, s58, v146
	s_add_i32 s55, s55, s35
	ds_read_b128 v[210:213], v144
	ds_read_b128 v[214:217], v144 offset:1024
	ds_read_b128 v[218:221], v144 offset:2048
	ds_read_b128 v[222:225], v144 offset:3072
	s_add_u32 s64, s22, 0x80
	s_addc_u32 s65, s23, 0
	s_mov_b32 m0, s55
	s_nop 0
	global_load_lds_dwordx4 v134, s[22:23]
	s_add_i32 m0, s55, 0x2000
	s_nop 0
	global_load_lds_dwordx4 v130, s[22:23]
	s_barrier
	s_waitcnt lgkmcnt(0)
	s_waitcnt lgkmcnt(0)
	v_mfma_f32_16x16x32_bf16 v[126:129], v[210:213], v[166:169], 0
	v_mfma_f32_16x16x32_bf16 v[122:125], v[218:221], v[166:169], 0
	v_mfma_f32_16x16x32_bf16 v[118:121], v[210:213], v[174:177], 0
	v_mfma_f32_16x16x32_bf16 v[114:117], v[218:221], v[174:177], 0
	v_mfma_f32_16x16x32_bf16 v[110:113], v[210:213], v[194:197], 0
	v_mfma_f32_16x16x32_bf16 v[106:109], v[218:221], v[194:197], 0
	v_mfma_f32_16x16x32_bf16 v[102:105], v[210:213], v[202:205], 0
	v_mfma_f32_16x16x32_bf16 v[98:101], v[218:221], v[202:205], 0
	v_mfma_f32_16x16x32_bf16 v[126:129], v[214:217], v[170:173], v[126:129]
	v_mfma_f32_16x16x32_bf16 v[122:125], v[222:225], v[170:173], v[122:125]
	v_mfma_f32_16x16x32_bf16 v[118:121], v[214:217], v[190:193], v[118:121]
	v_mfma_f32_16x16x32_bf16 v[114:117], v[222:225], v[190:193], v[114:117]
	v_mfma_f32_16x16x32_bf16 v[110:113], v[214:217], v[198:201], v[110:113]
	v_mfma_f32_16x16x32_bf16 v[106:109], v[222:225], v[198:201], v[106:109]
	v_mfma_f32_16x16x32_bf16 v[102:105], v[214:217], v[206:209], v[102:105]
	v_mfma_f32_16x16x32_bf16 v[98:101], v[222:225], v[206:209], v[98:101]
	s_barrier
	s_mov_b32 m0, s41
	s_add_u32 s62, s24, 0x80
	s_addc_u32 s63, s25, 0
	ds_read_b128 v[166:169], v148 offset:16384
	ds_read_b128 v[170:173], v148 offset:17408
	ds_read_b128 v[174:177], v148 offset:18432
	ds_read_b128 v[190:193], v148 offset:19456
	ds_read_b128 v[194:197], v148 offset:20480
	ds_read_b128 v[198:201], v148 offset:21504
	ds_read_b128 v[202:205], v148 offset:22528
	ds_read_b128 v[206:209], v148 offset:23552
	global_load_lds_dwordx4 v136, s[24:25]
	s_mov_b32 m0, s42
	s_nop 0
	global_load_lds_dwordx4 v132, s[24:25]
	s_barrier
	s_waitcnt lgkmcnt(0)
	s_waitcnt lgkmcnt(0)
	v_mfma_f32_16x16x32_bf16 v[34:37], v[150:153], v[166:169], 0
	v_mfma_f32_16x16x32_bf16 v[26:29], v[158:161], v[166:169], 0
	v_mfma_f32_16x16x32_bf16 v[22:25], v[150:153], v[174:177], 0
	v_mfma_f32_16x16x32_bf16 v[18:21], v[158:161], v[174:177], 0
	v_mfma_f32_16x16x32_bf16 v[14:17], v[150:153], v[194:197], 0
	v_mfma_f32_16x16x32_bf16 v[10:13], v[158:161], v[194:197], 0
	v_mfma_f32_16x16x32_bf16 v[6:9], v[150:153], v[202:205], 0
	v_mfma_f32_16x16x32_bf16 v[2:5], v[158:161], v[202:205], 0
	v_mfma_f32_16x16x32_bf16 v[34:37], v[154:157], v[170:173], v[34:37]
	v_mfma_f32_16x16x32_bf16 v[26:29], v[162:165], v[170:173], v[26:29]
	v_mfma_f32_16x16x32_bf16 v[22:25], v[154:157], v[190:193], v[22:25]
	v_mfma_f32_16x16x32_bf16 v[18:21], v[162:165], v[190:193], v[18:21]
	v_mfma_f32_16x16x32_bf16 v[14:17], v[154:157], v[198:201], v[14:17]
	v_mfma_f32_16x16x32_bf16 v[10:13], v[162:165], v[198:201], v[10:13]
	v_mfma_f32_16x16x32_bf16 v[6:9], v[154:157], v[206:209], v[6:9]
	v_mfma_f32_16x16x32_bf16 v[2:5], v[162:165], v[206:209], v[2:5]
	s_barrier
	s_add_u32 s56, s22, 0x40000
	s_addc_u32 s57, s23, 0
	s_add_i32 s55, s58, s35
	s_mov_b32 m0, s55
	s_nop 0
	global_load_lds_dwordx4 v134, s[56:57]
	s_add_i32 m0, s55, 0x2000
	s_nop 0
	global_load_lds_dwordx4 v130, s[56:57]
	s_waitcnt vmcnt(6)
	s_barrier
	v_mfma_f32_16x16x32_bf16 v[94:97], v[210:213], v[166:169], 0
	v_mfma_f32_16x16x32_bf16 v[90:93], v[218:221], v[166:169], 0
	v_mfma_f32_16x16x32_bf16 v[70:73], v[210:213], v[174:177], 0
	v_mfma_f32_16x16x32_bf16 v[66:69], v[218:221], v[174:177], 0
	v_mfma_f32_16x16x32_bf16 v[46:49], v[210:213], v[194:197], 0
	v_mfma_f32_16x16x32_bf16 v[42:45], v[218:221], v[194:197], 0
	v_mfma_f32_16x16x32_bf16 v[38:41], v[210:213], v[202:205], 0
	v_mfma_f32_16x16x32_bf16 v[30:33], v[218:221], v[202:205], 0
	v_mfma_f32_16x16x32_bf16 v[94:97], v[214:217], v[170:173], v[94:97]
	v_mfma_f32_16x16x32_bf16 v[90:93], v[222:225], v[170:173], v[90:93]
	v_mfma_f32_16x16x32_bf16 v[70:73], v[214:217], v[190:193], v[70:73]
	v_mfma_f32_16x16x32_bf16 v[66:69], v[222:225], v[190:193], v[66:69]
	v_mfma_f32_16x16x32_bf16 v[46:49], v[214:217], v[198:201], v[46:49]
	v_mfma_f32_16x16x32_bf16 v[42:45], v[222:225], v[198:201], v[42:45]
	v_mfma_f32_16x16x32_bf16 v[38:41], v[214:217], v[206:209], v[38:41]
	v_mfma_f32_16x16x32_bf16 v[30:33], v[222:225], v[206:209], v[30:33]
	s_barrier
	s_add_i32 s55, 0, 0x18000
	v_add_u32_e32 v149, s55, v146
	ds_read_b128 v[150:153], v149
	ds_read_b128 v[154:157], v149 offset:1024
	ds_read_b128 v[158:161], v149 offset:2048
	ds_read_b128 v[162:165], v149 offset:3072
	s_add_u32 s24, s24, 0x40000
	s_addc_u32 s25, s25, 0
	s_mov_b32 m0, s43
	ds_read_b128 v[166:169], v148 offset:32768
	ds_read_b128 v[170:173], v148 offset:33792
	ds_read_b128 v[174:177], v148 offset:34816
	ds_read_b128 v[190:193], v148 offset:35840
	ds_read_b128 v[194:197], v148 offset:36864
	ds_read_b128 v[198:201], v148 offset:37888
	ds_read_b128 v[202:205], v148 offset:38912
	ds_read_b128 v[206:209], v148 offset:39936
	global_load_lds_dwordx4 v136, s[24:25]
	s_mov_b32 m0, s44
	s_nop 0
	global_load_lds_dwordx4 v132, s[24:25]
	s_waitcnt lgkmcnt(8)
	s_barrier
	s_waitcnt lgkmcnt(0)
	s_waitcnt lgkmcnt(0)
	v_mfma_f32_16x16x32_bf16 v[86:89], v[150:153], v[166:169], v[86:89]
	v_mfma_f32_16x16x32_bf16 v[82:85], v[158:161], v[166:169], v[82:85]
	v_mfma_f32_16x16x32_bf16 v[78:81], v[150:153], v[174:177], v[78:81]
	v_mfma_f32_16x16x32_bf16 v[74:77], v[158:161], v[174:177], v[74:77]
	v_mfma_f32_16x16x32_bf16 v[62:65], v[150:153], v[194:197], v[62:65]
	v_mfma_f32_16x16x32_bf16 v[58:61], v[158:161], v[194:197], v[58:61]
	v_mfma_f32_16x16x32_bf16 v[54:57], v[150:153], v[202:205], v[54:57]
	v_mfma_f32_16x16x32_bf16 v[50:53], v[158:161], v[202:205], v[50:53]
	v_mfma_f32_16x16x32_bf16 v[86:89], v[154:157], v[170:173], v[86:89]
	v_mfma_f32_16x16x32_bf16 v[82:85], v[162:165], v[170:173], v[82:85]
	v_mfma_f32_16x16x32_bf16 v[78:81], v[154:157], v[190:193], v[78:81]
	v_mfma_f32_16x16x32_bf16 v[74:77], v[162:165], v[190:193], v[74:77]
	v_mfma_f32_16x16x32_bf16 v[62:65], v[154:157], v[198:201], v[62:65]
	v_mfma_f32_16x16x32_bf16 v[58:61], v[162:165], v[198:201], v[58:61]
	v_mfma_f32_16x16x32_bf16 v[54:57], v[154:157], v[206:209], v[54:57]
	v_mfma_f32_16x16x32_bf16 v[50:53], v[162:165], v[206:209], v[50:53]
	s_barrier
	s_add_i32 s24, 0, 0x1c000
	s_add_i32 s25, s55, s35
	v_add_u32_e32 v149, s24, v146
	s_mov_b32 m0, s25
	ds_read_b128 v[210:213], v149
	ds_read_b128 v[214:217], v149 offset:1024
	ds_read_b128 v[218:221], v149 offset:2048
	ds_read_b128 v[222:225], v149 offset:3072
	global_load_lds_dwordx4 v134, s[64:65]
	s_add_i32 m0, s25, 0x2000
	s_nop 0
	global_load_lds_dwordx4 v130, s[64:65]
	s_barrier
	s_waitcnt lgkmcnt(0)
	s_waitcnt lgkmcnt(0)
	v_mfma_f32_16x16x32_bf16 v[126:129], v[210:213], v[166:169], v[126:129]
	v_mfma_f32_16x16x32_bf16 v[122:125], v[218:221], v[166:169], v[122:125]
	v_mfma_f32_16x16x32_bf16 v[118:121], v[210:213], v[174:177], v[118:121]
	v_mfma_f32_16x16x32_bf16 v[114:117], v[218:221], v[174:177], v[114:117]
	v_mfma_f32_16x16x32_bf16 v[110:113], v[210:213], v[194:197], v[110:113]
	v_mfma_f32_16x16x32_bf16 v[106:109], v[218:221], v[194:197], v[106:109]
	v_mfma_f32_16x16x32_bf16 v[102:105], v[210:213], v[202:205], v[102:105]
	v_mfma_f32_16x16x32_bf16 v[98:101], v[218:221], v[202:205], v[98:101]
	v_mfma_f32_16x16x32_bf16 v[126:129], v[214:217], v[170:173], v[126:129]
	v_mfma_f32_16x16x32_bf16 v[122:125], v[222:225], v[170:173], v[122:125]
	v_mfma_f32_16x16x32_bf16 v[118:121], v[214:217], v[190:193], v[118:121]
	v_mfma_f32_16x16x32_bf16 v[114:117], v[222:225], v[190:193], v[114:117]
	v_mfma_f32_16x16x32_bf16 v[110:113], v[214:217], v[198:201], v[110:113]
	v_mfma_f32_16x16x32_bf16 v[106:109], v[222:225], v[198:201], v[106:109]
	v_mfma_f32_16x16x32_bf16 v[102:105], v[214:217], v[206:209], v[102:105]
	v_mfma_f32_16x16x32_bf16 v[98:101], v[222:225], v[206:209], v[98:101]
	s_barrier
	s_mov_b32 m0, s46
	ds_read_b128 v[166:169], v148 offset:49152
	ds_read_b128 v[170:173], v148 offset:50176
	ds_read_b128 v[174:177], v148 offset:51200
	ds_read_b128 v[190:193], v148 offset:52224
	ds_read_b128 v[194:197], v148 offset:53248
	ds_read_b128 v[198:201], v148 offset:54272
	ds_read_b128 v[202:205], v148 offset:55296
	ds_read_b128 v[206:209], v148 offset:56320
	global_load_lds_dwordx4 v136, s[62:63]
	s_mov_b32 m0, s47
	s_nop 0
	global_load_lds_dwordx4 v132, s[62:63]
	s_barrier
	s_waitcnt lgkmcnt(0)
	s_waitcnt lgkmcnt(0)
	v_mfma_f32_16x16x32_bf16 v[34:37], v[150:153], v[166:169], v[34:37]
	v_mfma_f32_16x16x32_bf16 v[26:29], v[158:161], v[166:169], v[26:29]
	v_mfma_f32_16x16x32_bf16 v[22:25], v[150:153], v[174:177], v[22:25]
	v_mfma_f32_16x16x32_bf16 v[18:21], v[158:161], v[174:177], v[18:21]
	v_mfma_f32_16x16x32_bf16 v[14:17], v[150:153], v[194:197], v[14:17]
	v_mfma_f32_16x16x32_bf16 v[10:13], v[158:161], v[194:197], v[10:13]
	v_mfma_f32_16x16x32_bf16 v[6:9], v[150:153], v[202:205], v[6:9]
	v_mfma_f32_16x16x32_bf16 v[2:5], v[158:161], v[202:205], v[2:5]
	v_mfma_f32_16x16x32_bf16 v[34:37], v[154:157], v[170:173], v[34:37]
	v_mfma_f32_16x16x32_bf16 v[26:29], v[162:165], v[170:173], v[26:29]
	v_mfma_f32_16x16x32_bf16 v[22:25], v[154:157], v[190:193], v[22:25]
	v_mfma_f32_16x16x32_bf16 v[18:21], v[162:165], v[190:193], v[18:21]
	v_mfma_f32_16x16x32_bf16 v[14:17], v[154:157], v[198:201], v[14:17]
	v_mfma_f32_16x16x32_bf16 v[10:13], v[162:165], v[198:201], v[10:13]
	v_mfma_f32_16x16x32_bf16 v[6:9], v[154:157], v[206:209], v[6:9]
	v_mfma_f32_16x16x32_bf16 v[2:5], v[162:165], v[206:209], v[2:5]
	s_barrier
	s_add_u32 s22, s22, 0x40080
	s_addc_u32 s23, s23, 0
	s_add_i32 s24, s24, s35
	s_mov_b32 m0, s24
	s_nop 0
	global_load_lds_dwordx4 v134, s[22:23]
	v_lshl_add_u64 v[144:145], s[22:23], 0, v[130:131]
	s_add_i32 m0, s24, 0x2000
	s_nop 0
	global_load_lds_dwordx4 v[144:145], off
	s_waitcnt vmcnt(6)
	s_barrier
	v_mfma_f32_16x16x32_bf16 v[94:97], v[210:213], v[166:169], v[94:97]
	v_mfma_f32_16x16x32_bf16 v[90:93], v[218:221], v[166:169], v[90:93]
	v_mfma_f32_16x16x32_bf16 v[70:73], v[210:213], v[174:177], v[70:73]
	v_mfma_f32_16x16x32_bf16 v[66:69], v[218:221], v[174:177], v[66:69]
	v_mfma_f32_16x16x32_bf16 v[46:49], v[210:213], v[194:197], v[46:49]
	v_mfma_f32_16x16x32_bf16 v[42:45], v[218:221], v[194:197], v[42:45]
	v_mfma_f32_16x16x32_bf16 v[38:41], v[210:213], v[202:205], v[38:41]
	v_mfma_f32_16x16x32_bf16 v[30:33], v[218:221], v[202:205], v[30:33]
	v_mfma_f32_16x16x32_bf16 v[94:97], v[214:217], v[170:173], v[94:97]
	v_mfma_f32_16x16x32_bf16 v[90:93], v[222:225], v[170:173], v[90:93]
	v_mfma_f32_16x16x32_bf16 v[70:73], v[214:217], v[190:193], v[70:73]
	v_mfma_f32_16x16x32_bf16 v[66:69], v[222:225], v[190:193], v[66:69]
	v_mfma_f32_16x16x32_bf16 v[46:49], v[214:217], v[198:201], v[46:49]
	v_mfma_f32_16x16x32_bf16 v[42:45], v[222:225], v[198:201], v[42:45]
	v_mfma_f32_16x16x32_bf16 v[38:41], v[214:217], v[206:209], v[38:41]
	v_mfma_f32_16x16x32_bf16 v[30:33], v[222:225], v[206:209], v[30:33]
	s_barrier
	s_add_i32 s54, s54, 2
	s_add_u32 s20, s20, 0x100
	s_addc_u32 s21, s21, 0
	s_add_u32 s52, s52, 0x100
	s_addc_u32 s53, s53, 0

.LBB0_1407:
	s_ashr_i32 s3, s2, 31
	s_lshl_b64 s[12:13], s[2:3], 20
	s_add_u32 s12, s24, s12
	s_addc_u32 s13, s25, s13
	s_and_b64 s[6:7], s[6:7], exec
	s_cselect_b32 s3, s13, s17
	s_cselect_b32 s44, s12, s16
	s_add_u32 s45, s16, 0x100
	s_addc_u32 s46, s17, 0
	s_add_u32 s6, s14, 0x80
	s_addc_u32 s7, s15, 0
	v_lshl_add_u64 v[142:143], s[6:7], 0, v[138:139]
	v_lshl_add_u64 v[144:145], s[6:7], 0, v[140:141]
	s_mov_b32 s47, -2
	s_mov_b64 s[6:7], 0
	s_add_u32 s16, s14, s6
	s_addc_u32 s17, s15, s7
	s_add_u32 s16, s16, 0x100
	s_addc_u32 s17, s17, 0
	s_add_u32 s48, s45, s6
	s_addc_u32 s49, s46, s7
	s_add_i32 s50, 0, 0x10000
	v_add_u32_e32 v158, s50, v164
	ds_read_b128 v[146:149], v158
	ds_read_b128 v[150:153], v158 offset:1024
	ds_read_b128 v[154:157], v158 offset:2048
	ds_read_b128 v[158:161], v158 offset:3072
	s_cmpk_eq_i32 s6, 0xf00
	s_cselect_b32 s19, s11, s17
	s_cselect_b32 s18, s10, s16
	s_cselect_b32 s17, s3, s49
	s_cselect_b32 s16, s44, s48
	v_lshl_add_u64 v[162:163], v[142:143], 0, s[6:7]
	s_add_i32 m0, s30, 0xc000
	ds_read_b128 v[168:171], v166
	ds_read_b128 v[172:175], v166 offset:1024
	ds_read_b128 v[186:189], v166 offset:2048
	ds_read_b128 v[190:193], v166 offset:3072
	ds_read_b128 v[194:197], v166 offset:4096
	ds_read_b128 v[198:201], v166 offset:5120
	ds_read_b128 v[202:205], v166 offset:6144
	ds_read_b128 v[206:209], v166 offset:7168
	global_load_lds_dwordx4 v[162:163], off
	v_lshl_add_u64 v[162:163], v[144:145], 0, s[6:7]
	s_add_i32 m0, s30, 0xe000
	s_nop 0
	global_load_lds_dwordx4 v[162:163], off
	s_waitcnt lgkmcnt(8)
	s_barrier
	s_waitcnt lgkmcnt(0)
	s_waitcnt lgkmcnt(0)
	v_mfma_f32_16x16x32_bf16 v[126:129], v[146:149], v[168:171], 0
	v_mfma_f32_16x16x32_bf16 v[122:125], v[154:157], v[168:171], 0
	v_mfma_f32_16x16x32_bf16 v[110:113], v[146:149], v[186:189], 0
	v_mfma_f32_16x16x32_bf16 v[106:109], v[154:157], v[186:189], 0
	v_mfma_f32_16x16x32_bf16 v[94:97], v[146:149], v[194:197], 0
	v_mfma_f32_16x16x32_bf16 v[90:93], v[154:157], v[194:197], 0
	v_mfma_f32_16x16x32_bf16 v[78:81], v[146:149], v[202:205], 0
	v_mfma_f32_16x16x32_bf16 v[74:77], v[154:157], v[202:205], 0
	v_mfma_f32_16x16x32_bf16 v[126:129], v[150:153], v[172:175], v[126:129]
	v_mfma_f32_16x16x32_bf16 v[122:125], v[158:161], v[172:175], v[122:125]
	v_mfma_f32_16x16x32_bf16 v[110:113], v[150:153], v[190:193], v[110:113]
	v_mfma_f32_16x16x32_bf16 v[106:109], v[158:161], v[190:193], v[106:109]
	v_mfma_f32_16x16x32_bf16 v[94:97], v[150:153], v[198:201], v[94:97]
	v_mfma_f32_16x16x32_bf16 v[90:93], v[158:161], v[198:201], v[90:93]
	v_mfma_f32_16x16x32_bf16 v[78:81], v[150:153], v[206:209], v[78:81]
	v_mfma_f32_16x16x32_bf16 v[74:77], v[158:161], v[206:209], v[74:77]
	s_barrier
	s_add_i32 s51, 0, 0x14000
	v_add_u32_e32 v162, s51, v164
	s_add_i32 s48, s50, s29
	ds_read_b128 v[210:213], v162
	ds_read_b128 v[214:217], v162 offset:1024
	ds_read_b128 v[218:221], v162 offset:2048
	ds_read_b128 v[222:225], v162 offset:3072
	s_add_u32 s64, s16, 0x80
	s_addc_u32 s65, s17, 0
	s_mov_b32 m0, s48
	s_nop 0
	global_load_lds_dwordx4 v132, s[16:17]
	s_add_i32 m0, s48, 0x2000
	s_nop 0
	global_load_lds_dwordx4 v136, s[16:17]
	s_barrier
	s_waitcnt lgkmcnt(0)
	s_waitcnt lgkmcnt(0)
	v_mfma_f32_16x16x32_bf16 v[118:121], v[210:213], v[168:171], 0
	v_mfma_f32_16x16x32_bf16 v[114:117], v[218:221], v[168:171], 0
	v_mfma_f32_16x16x32_bf16 v[102:105], v[210:213], v[186:189], 0
	v_mfma_f32_16x16x32_bf16 v[98:101], v[218:221], v[186:189], 0
	v_mfma_f32_16x16x32_bf16 v[86:89], v[210:213], v[194:197], 0
	v_mfma_f32_16x16x32_bf16 v[82:85], v[218:221], v[194:197], 0
	v_mfma_f32_16x16x32_bf16 v[70:73], v[210:213], v[202:205], 0
	v_mfma_f32_16x16x32_bf16 v[66:69], v[218:221], v[202:205], 0
	v_mfma_f32_16x16x32_bf16 v[118:121], v[214:217], v[172:175], v[118:121]
	v_mfma_f32_16x16x32_bf16 v[114:117], v[222:225], v[172:175], v[114:117]
	v_mfma_f32_16x16x32_bf16 v[102:105], v[214:217], v[190:193], v[102:105]
	v_mfma_f32_16x16x32_bf16 v[98:101], v[222:225], v[190:193], v[98:101]
	v_mfma_f32_16x16x32_bf16 v[86:89], v[214:217], v[198:201], v[86:89]
	v_mfma_f32_16x16x32_bf16 v[82:85], v[222:225], v[198:201], v[82:85]
	v_mfma_f32_16x16x32_bf16 v[70:73], v[214:217], v[206:209], v[70:73]
	v_mfma_f32_16x16x32_bf16 v[66:69], v[222:225], v[206:209], v[66:69]
	s_barrier
	s_mov_b32 m0, s30
	s_add_u32 s62, s18, 0x80
	s_addc_u32 s63, s19, 0
	ds_read_b128 v[168:171], v166 offset:16384
	ds_read_b128 v[172:175], v166 offset:17408
	ds_read_b128 v[186:189], v166 offset:18432
	ds_read_b128 v[190:193], v166 offset:19456
	ds_read_b128 v[194:197], v166 offset:20480
	ds_read_b128 v[198:201], v166 offset:21504
	ds_read_b128 v[202:205], v166 offset:22528
	ds_read_b128 v[206:209], v166 offset:23552
	global_load_lds_dwordx4 v130, s[18:19]
	s_mov_b32 m0, s31
	s_nop 0
	global_load_lds_dwordx4 v134, s[18:19]
	s_barrier
	s_waitcnt lgkmcnt(0)
	s_waitcnt lgkmcnt(0)
	v_mfma_f32_16x16x32_bf16 v[62:65], v[146:149], v[168:171], 0
	v_mfma_f32_16x16x32_bf16 v[58:61], v[154:157], v[168:171], 0
	v_mfma_f32_16x16x32_bf16 v[46:49], v[146:149], v[186:189], 0
	v_mfma_f32_16x16x32_bf16 v[42:45], v[154:157], v[186:189], 0
	v_mfma_f32_16x16x32_bf16 v[30:33], v[146:149], v[194:197], 0
	v_mfma_f32_16x16x32_bf16 v[26:29], v[154:157], v[194:197], 0
	v_mfma_f32_16x16x32_bf16 v[14:17], v[146:149], v[202:205], 0
	v_mfma_f32_16x16x32_bf16 v[10:13], v[154:157], v[202:205], 0
	v_mfma_f32_16x16x32_bf16 v[62:65], v[150:153], v[172:175], v[62:65]
	v_mfma_f32_16x16x32_bf16 v[58:61], v[158:161], v[172:175], v[58:61]
	v_mfma_f32_16x16x32_bf16 v[46:49], v[150:153], v[190:193], v[46:49]
	v_mfma_f32_16x16x32_bf16 v[42:45], v[158:161], v[190:193], v[42:45]
	v_mfma_f32_16x16x32_bf16 v[30:33], v[150:153], v[198:201], v[30:33]
	v_mfma_f32_16x16x32_bf16 v[26:29], v[158:161], v[198:201], v[26:29]
	v_mfma_f32_16x16x32_bf16 v[14:17], v[150:153], v[206:209], v[14:17]
	v_mfma_f32_16x16x32_bf16 v[10:13], v[158:161], v[206:209], v[10:13]
	s_barrier
	s_add_u32 s48, s16, 0x80000
	s_addc_u32 s49, s17, 0
	s_add_i32 s50, s51, s29
	s_mov_b32 m0, s50
	s_nop 0
	global_load_lds_dwordx4 v132, s[48:49]
	s_add_i32 m0, s50, 0x2000
	s_nop 0
	global_load_lds_dwordx4 v136, s[48:49]
	s_waitcnt vmcnt(6)
	s_barrier
	v_mfma_f32_16x16x32_bf16 v[54:57], v[210:213], v[168:171], 0
	v_mfma_f32_16x16x32_bf16 v[50:53], v[218:221], v[168:171], 0
	v_mfma_f32_16x16x32_bf16 v[38:41], v[210:213], v[186:189], 0
	v_mfma_f32_16x16x32_bf16 v[34:37], v[218:221], v[186:189], 0
	v_mfma_f32_16x16x32_bf16 v[22:25], v[210:213], v[194:197], 0
	v_mfma_f32_16x16x32_bf16 v[18:21], v[218:221], v[194:197], 0
	v_mfma_f32_16x16x32_bf16 v[6:9], v[210:213], v[202:205], 0
	v_mfma_f32_16x16x32_bf16 v[2:5], v[218:221], v[202:205], 0
	v_mfma_f32_16x16x32_bf16 v[54:57], v[214:217], v[172:175], v[54:57]
	v_mfma_f32_16x16x32_bf16 v[50:53], v[222:225], v[172:175], v[50:53]
	v_mfma_f32_16x16x32_bf16 v[38:41], v[214:217], v[190:193], v[38:41]
	v_mfma_f32_16x16x32_bf16 v[34:37], v[222:225], v[190:193], v[34:37]
	v_mfma_f32_16x16x32_bf16 v[22:25], v[214:217], v[198:201], v[22:25]
	v_mfma_f32_16x16x32_bf16 v[18:21], v[222:225], v[198:201], v[18:21]
	v_mfma_f32_16x16x32_bf16 v[6:9], v[214:217], v[206:209], v[6:9]
	v_mfma_f32_16x16x32_bf16 v[2:5], v[222:225], v[206:209], v[2:5]
	s_barrier
	s_add_i32 s48, 0, 0x18000
	v_add_u32_e32 v158, s48, v164
	ds_read_b128 v[146:149], v158
	ds_read_b128 v[150:153], v158 offset:1024
	ds_read_b128 v[154:157], v158 offset:2048
	ds_read_b128 v[158:161], v158 offset:3072
	s_add_u32 s18, s18, s80
	s_addc_u32 s19, s19, 0
	s_mov_b32 m0, s34
	ds_read_b128 v[168:171], v166 offset:32768
	ds_read_b128 v[172:175], v166 offset:33792
	ds_read_b128 v[186:189], v166 offset:34816
	ds_read_b128 v[190:193], v166 offset:35840
	ds_read_b128 v[194:197], v166 offset:36864
	ds_read_b128 v[198:201], v166 offset:37888
	ds_read_b128 v[202:205], v166 offset:38912
	ds_read_b128 v[206:209], v166 offset:39936
	global_load_lds_dwordx4 v130, s[18:19]
	s_mov_b32 m0, s35
	s_nop 0
	global_load_lds_dwordx4 v134, s[18:19]
	s_waitcnt lgkmcnt(8)
	s_barrier
	s_waitcnt lgkmcnt(0)
	s_waitcnt lgkmcnt(0)
	v_mfma_f32_16x16x32_bf16 v[126:129], v[146:149], v[168:171], v[126:129]
	v_mfma_f32_16x16x32_bf16 v[122:125], v[154:157], v[168:171], v[122:125]
	v_mfma_f32_16x16x32_bf16 v[110:113], v[146:149], v[186:189], v[110:113]
	v_mfma_f32_16x16x32_bf16 v[106:109], v[154:157], v[186:189], v[106:109]
	v_mfma_f32_16x16x32_bf16 v[94:97], v[146:149], v[194:197], v[94:97]
	v_mfma_f32_16x16x32_bf16 v[90:93], v[154:157], v[194:197], v[90:93]
	v_mfma_f32_16x16x32_bf16 v[78:81], v[146:149], v[202:205], v[78:81]
	v_mfma_f32_16x16x32_bf16 v[74:77], v[154:157], v[202:205], v[74:77]
	v_mfma_f32_16x16x32_bf16 v[126:129], v[150:153], v[172:175], v[126:129]
	v_mfma_f32_16x16x32_bf16 v[122:125], v[158:161], v[172:175], v[122:125]
	v_mfma_f32_16x16x32_bf16 v[110:113], v[150:153], v[190:193], v[110:113]
	v_mfma_f32_16x16x32_bf16 v[106:109], v[158:161], v[190:193], v[106:109]
	v_mfma_f32_16x16x32_bf16 v[94:97], v[150:153], v[198:201], v[94:97]
	v_mfma_f32_16x16x32_bf16 v[90:93], v[158:161], v[198:201], v[90:93]
	v_mfma_f32_16x16x32_bf16 v[78:81], v[150:153], v[206:209], v[78:81]
	v_mfma_f32_16x16x32_bf16 v[74:77], v[158:161], v[206:209], v[74:77]
	s_barrier
	s_add_i32 s18, 0, 0x1c000
	s_add_i32 s19, s48, s29
	v_add_u32_e32 v167, s18, v164
	s_mov_b32 m0, s19
	ds_read_b128 v[210:213], v167
	ds_read_b128 v[214:217], v167 offset:1024
	ds_read_b128 v[218:221], v167 offset:2048
	ds_read_b128 v[222:225], v167 offset:3072
	global_load_lds_dwordx4 v132, s[64:65]
	s_add_i32 m0, s19, 0x2000
	s_nop 0
	global_load_lds_dwordx4 v136, s[64:65]
	s_barrier
	s_waitcnt lgkmcnt(0)
	s_waitcnt lgkmcnt(0)
	v_mfma_f32_16x16x32_bf16 v[118:121], v[210:213], v[168:171], v[118:121]
	v_mfma_f32_16x16x32_bf16 v[114:117], v[218:221], v[168:171], v[114:117]
	v_mfma_f32_16x16x32_bf16 v[102:105], v[210:213], v[186:189], v[102:105]
	v_mfma_f32_16x16x32_bf16 v[98:101], v[218:221], v[186:189], v[98:101]
	v_mfma_f32_16x16x32_bf16 v[86:89], v[210:213], v[194:197], v[86:89]
	v_mfma_f32_16x16x32_bf16 v[82:85], v[218:221], v[194:197], v[82:85]
	v_mfma_f32_16x16x32_bf16 v[70:73], v[210:213], v[202:205], v[70:73]
	v_mfma_f32_16x16x32_bf16 v[66:69], v[218:221], v[202:205], v[66:69]
	v_mfma_f32_16x16x32_bf16 v[118:121], v[214:217], v[172:175], v[118:121]
	v_mfma_f32_16x16x32_bf16 v[114:117], v[222:225], v[172:175], v[114:117]
	v_mfma_f32_16x16x32_bf16 v[102:105], v[214:217], v[190:193], v[102:105]
	v_mfma_f32_16x16x32_bf16 v[98:101], v[222:225], v[190:193], v[98:101]
	v_mfma_f32_16x16x32_bf16 v[86:89], v[214:217], v[198:201], v[86:89]
	v_mfma_f32_16x16x32_bf16 v[82:85], v[222:225], v[198:201], v[82:85]
	v_mfma_f32_16x16x32_bf16 v[70:73], v[214:217], v[206:209], v[70:73]
	v_mfma_f32_16x16x32_bf16 v[66:69], v[222:225], v[206:209], v[66:69]
	s_barrier
	s_mov_b32 m0, s38
	ds_read_b128 v[168:171], v166 offset:49152
	ds_read_b128 v[172:175], v166 offset:50176
	ds_read_b128 v[186:189], v166 offset:51200
	ds_read_b128 v[190:193], v166 offset:52224
	ds_read_b128 v[194:197], v166 offset:53248
	ds_read_b128 v[198:201], v166 offset:54272
	ds_read_b128 v[202:205], v166 offset:55296
	ds_read_b128 v[206:209], v166 offset:56320
	global_load_lds_dwordx4 v130, s[62:63]
	s_mov_b32 m0, s39
	s_nop 0
	global_load_lds_dwordx4 v134, s[62:63]
	s_barrier
	s_waitcnt lgkmcnt(0)
	s_waitcnt lgkmcnt(0)
	v_mfma_f32_16x16x32_bf16 v[62:65], v[146:149], v[168:171], v[62:65]
	v_mfma_f32_16x16x32_bf16 v[58:61], v[154:157], v[168:171], v[58:61]
	v_mfma_f32_16x16x32_bf16 v[46:49], v[146:149], v[186:189], v[46:49]
	v_mfma_f32_16x16x32_bf16 v[42:45], v[154:157], v[186:189], v[42:45]
	v_mfma_f32_16x16x32_bf16 v[30:33], v[146:149], v[194:197], v[30:33]
	v_mfma_f32_16x16x32_bf16 v[26:29], v[154:157], v[194:197], v[26:29]
	v_mfma_f32_16x16x32_bf16 v[14:17], v[146:149], v[202:205], v[14:17]
	v_mfma_f32_16x16x32_bf16 v[10:13], v[154:157], v[202:205], v[10:13]
	v_mfma_f32_16x16x32_bf16 v[62:65], v[150:153], v[172:175], v[62:65]
	v_mfma_f32_16x16x32_bf16 v[58:61], v[158:161], v[172:175], v[58:61]
	v_mfma_f32_16x16x32_bf16 v[46:49], v[150:153], v[190:193], v[46:49]
	v_mfma_f32_16x16x32_bf16 v[42:45], v[158:161], v[190:193], v[42:45]
	v_mfma_f32_16x16x32_bf16 v[30:33], v[150:153], v[198:201], v[30:33]
	v_mfma_f32_16x16x32_bf16 v[26:29], v[158:161], v[198:201], v[26:29]
	v_mfma_f32_16x16x32_bf16 v[14:17], v[150:153], v[206:209], v[14:17]
	v_mfma_f32_16x16x32_bf16 v[10:13], v[158:161], v[206:209], v[10:13]
	s_barrier
	s_add_u32 s16, s16, 0x80080
	s_addc_u32 s17, s17, 0
	s_add_i32 s18, s18, s29
	s_mov_b32 m0, s18
	s_nop 0
	global_load_lds_dwordx4 v132, s[16:17]
	s_add_i32 m0, s18, 0x2000
	s_nop 0
	global_load_lds_dwordx4 v136, s[16:17]
	s_waitcnt vmcnt(6)
	s_barrier
	v_mfma_f32_16x16x32_bf16 v[54:57], v[210:213], v[168:171], v[54:57]
	v_mfma_f32_16x16x32_bf16 v[50:53], v[218:221], v[168:171], v[50:53]
	v_mfma_f32_16x16x32_bf16 v[38:41], v[210:213], v[186:189], v[38:41]
	v_mfma_f32_16x16x32_bf16 v[34:37], v[218:221], v[186:189], v[34:37]
	v_mfma_f32_16x16x32_bf16 v[22:25], v[210:213], v[194:197], v[22:25]
	v_mfma_f32_16x16x32_bf16 v[18:21], v[218:221], v[194:197], v[18:21]
	v_mfma_f32_16x16x32_bf16 v[6:9], v[210:213], v[202:205], v[6:9]
	v_mfma_f32_16x16x32_bf16 v[2:5], v[218:221], v[202:205], v[2:5]
	v_mfma_f32_16x16x32_bf16 v[54:57], v[214:217], v[172:175], v[54:57]
	v_mfma_f32_16x16x32_bf16 v[50:53], v[222:225], v[172:175], v[50:53]
	v_mfma_f32_16x16x32_bf16 v[38:41], v[214:217], v[190:193], v[38:41]
	v_mfma_f32_16x16x32_bf16 v[34:37], v[222:225], v[190:193], v[34:37]
	v_mfma_f32_16x16x32_bf16 v[22:25], v[214:217], v[198:201], v[22:25]
	v_mfma_f32_16x16x32_bf16 v[18:21], v[222:225], v[198:201], v[18:21]
	v_mfma_f32_16x16x32_bf16 v[6:9], v[214:217], v[206:209], v[6:9]
	v_mfma_f32_16x16x32_bf16 v[2:5], v[222:225], v[206:209], v[2:5]
	s_barrier
	s_add_i32 s47, s47, 2
	s_add_u32 s6, s6, 0x100
	s_addc_u32 s7, s7, 0
